# P1 row loop: x rows prefetched TWO rows ahead by LDS-DMA into two per-wave buffers (more bytes in flight)
# speedup vs baseline: 1.0027x; 1.0027x over previous
; #define GAS __attribute__((address_space(1)))
; template <int LO, int HI> __global__ void __launch_bounds__(NWAVES * 64, 2) fox_fwd(Args args) {
;     ...
;         const int m0 = gw * 16, b = m0 / T;
;         f32x4 gm[4], sh[4];
; #pragma unroll
;         for (int j = 0; j < 4; ++j) { const int col = P1COL(j); const f32x4 g = *(const f32x4*)(norm_g + col), scl = *(const f32x4*)(ADA + b * 3072 + 1024 + col);
;             gm[j] = g * (scl + 1.0f); sh[j] = *(const f32x4*)(ADA + b * 3072 + col); }
;         const float bfv = b_f[lane & 7]; f32x4 lsq[4];
; #pragma unroll
;         for (int k = 0; k < 4; ++k) lsq[k] = (f32x4){0.f, 0.f, 0.f, 0.f};
;         for (int r = 0; r < 16; ++r) { const int m = m0 + r;
;             const GAS float* xr = (const GAS float*)(x + (size_t)m * D);
;             f32x4 v[4]; float s2 = 0.f;
; #pragma unroll
;             for (int j = 0; j < 4; ++j) { v[j] = *(const GAS f32x4*)(xr + P1COL(j)); s2 += (v[j][0] * v[j][0] + v[j][1] * v[j][1]) + (v[j][2] * v[j][2] + v[j][3] * v[j][3]); }
.LBB0_130:
	s_or_b64 exec, exec, s[8:9]
	s_ashr_i32 s43, s15, 6
	s_lshl_b32 s8, s14, 3
	s_add_i32 s33, s8, s43
	s_ashr_i32 s8, s33, 31
	s_lshr_b32 s8, s8, 24
	s_add_i32 s8, s33, s8
	s_ashr_i32 s44, s8, 8
	s_mul_i32 s8, s44, 0xc00
	s_ashr_i32 s9, s8, 31
	s_lshl_b64 s[8:9], s[8:9], 2
	s_add_u32 s8, s26, s8
	s_addc_u32 s9, s27, s9
	s_add_u32 s10, s8, 0x1000
	s_addc_u32 s11, s9, 0
	s_lshl_b32 s28, s33, 4
	s_ashr_i32 s29, s28, 31
	s_lshl_b64 s[12:13], s[28:29], 12
	v_and_b32_e32 v1, 63, v34
	s_waitcnt lgkmcnt(0)
	s_add_u32 s30, s6, s12
	v_lshlrev_b32_e32 v54, 5, v1
	s_addc_u32 s31, s7, s13
	s_barrier
	global_load_dwordx4 v[26:29], v54, s[30:31]
	global_load_dwordx4 v[18:21], v54, s[30:31] offset:16
	global_load_dwordx4 v[22:25], v54, s[30:31] offset:2064
	global_load_dwordx4 v[30:33], v54, s[30:31] offset:2048
	global_load_dwordx4 v[38:41], v54, s[10:11] offset:16
	global_load_dwordx4 v[42:45], v54, s[10:11]
	v_mbcnt_lo_u32_b32 v3, -1, 0
	v_and_b32_e32 v2, 7, v34
	v_mbcnt_hi_u32_b32 v35, -1, v3
	v_or_b32_e32 v3, 0x800, v54
	v_lshlrev_b32_e32 v2, 2, v2
	global_load_dwordx4 v[46:49], v3, s[10:11] offset:16
	global_load_dwordx4 v[50:53], v3, s[10:11]
	global_load_dwordx4 v[58:61], v54, s[20:21] offset:16
	global_load_dwordx4 v[62:65], v54, s[20:21]
	global_load_dwordx4 v[74:77], v54, s[20:21] offset:2064
	global_load_dwordx4 v[78:81], v54, s[20:21] offset:2048
	global_load_dword v71, v2, s[4:5]
	v_xor_b32_e32 v83, 16, v35
	v_and_b32_e32 v68, 64, v35
	v_mov_b32_e32 v37, 0
	v_lshlrev_b32_e32 v36, 4, v1
	v_xor_b32_e32 v4, 1, v35
	v_add_u32_e32 v87, 64, v68
	s_mov_b64 s[12:13], 0x2000000
	v_xor_b32_e32 v5, 2, v35
	v_lshl_add_u64 v[2:3], s[26:27], 0, v[36:37]
	v_cmp_lt_i32_e32 vcc, v4, v87
	v_lshl_add_u64 v[56:57], v[2:3], 0, s[12:13]
	v_xor_b32_e32 v55, 4, v35
	v_cndmask_b32_e32 v2, v35, v4, vcc
	v_cmp_lt_i32_e32 vcc, v5, v87
	v_lshlrev_b32_e32 v165, 2, v2
	v_xor_b32_e32 v73, 8, v35
	v_cndmask_b32_e32 v88, v35, v5, vcc
	global_load_dwordx4 v[2:5], v54, s[8:9] offset:16
	global_load_dwordx4 v[6:9], v54, s[8:9]
	v_lshlrev_b32_e32 v169, 2, v88
	v_cmp_lt_i32_e32 vcc, v55, v87
	v_xor_b32_e32 v86, 32, v35
	v_mov_b32_e32 v69, 0x358637bd
	v_cndmask_b32_e32 v55, v35, v55, vcc
	v_lshlrev_b32_e32 v168, 2, v55
	v_cmp_lt_i32_e32 vcc, v73, v87
	s_mov_b32 s45, 0xf800000
	v_mov_b32_e32 v70, 0x260
	v_cndmask_b32_e32 v73, v35, v73, vcc
	v_lshlrev_b32_e32 v167, 2, v73
	v_cmp_lt_i32_e32 vcc, v83, v87
	s_lshl_b64 s[34:35], s[28:29], 11
	v_add_u32_e32 v72, 0, v54
	s_or_b32 s36, s28, 1
	s_ashr_i32 s37, s36, 31
	v_cmp_eq_u32_e64 s[10:11], 4, v1
	v_cmp_eq_u32_e64 s[12:13], 5, v1
	v_cmp_eq_u32_e64 s[14:15], 6, v1
	v_cmp_eq_u32_e64 s[16:17], 7, v1
	s_mov_b32 s29, 0xbfb8aa3b
	s_mov_b32 s46, 0x7f800000
	s_mov_b32 s47, 0x33800000
	s_movk_i32 s48, 0x2000
	s_mov_b64 s[38:39], 0x2800
	s_mov_b64 s[40:41], 0x800
	s_waitcnt vmcnt(14)
	v_pk_mul_f32 v[10:11], v[28:29], v[28:29]
	v_pk_mul_f32 v[12:13], v[26:27], v[26:27]
	s_waitcnt vmcnt(13)
	v_pk_mul_f32 v[14:15], v[20:21], v[20:21]
	v_pk_mul_f32 v[16:17], v[18:19], v[18:19]
	v_pk_mov_b32 v[84:85], v[12:13], v[10:11] op_sel:[1,0]
	v_mov_b32_e32 v13, v11
	v_pk_mov_b32 v[10:11], v[16:17], v[14:15] op_sel:[1,0]
	v_mov_b32_e32 v17, v15
	s_waitcnt vmcnt(11)
	v_mul_f32_e32 v66, v31, v31
	v_mul_f32_e32 v82, v33, v33
	v_pk_add_f32 v[12:13], v[84:85], v[12:13]
	v_pk_add_f32 v[10:11], v[10:11], v[16:17]
	v_mul_f32_e32 v89, v22, v22
	v_mul_f32_e32 v90, v23, v23
	v_mul_f32_e32 v91, v24, v24
	v_mul_f32_e32 v92, v25, v25
	v_pk_fma_f32 v[14:15], v[30:31], v[30:31], v[66:67] op_sel_hi:[1,1,0]
	v_pk_fma_f32 v[66:67], v[32:33], v[32:33], v[82:83] op_sel_hi:[1,1,0]
	v_pk_add_f32 v[12:13], v[12:13], v[12:13] op_sel:[0,1] op_sel_hi:[1,0]
	v_pk_add_f32 v[10:11], v[10:11], v[10:11] op_sel:[0,1] op_sel_hi:[1,0]
	v_mov_b32_e32 v15, v91
	v_mov_b32_e32 v67, v92
	v_mov_b32_e32 v13, v89
	v_mov_b32_e32 v11, v90
	v_pk_add_f32 v[14:15], v[14:15], v[66:67]
	v_pk_add_f32 v[10:11], v[12:13], v[10:11]
	v_cndmask_b32_e32 v82, v35, v83, vcc
	v_pk_add_f32 v[10:11], v[10:11], v[14:15]
	v_lshlrev_b32_e32 v166, 2, v82
	v_add_f32_e32 v66, v10, v11
	global_load_dwordx4 v[10:13], v54, s[8:9] offset:2064
	global_load_dwordx4 v[14:17], v54, s[8:9] offset:2048
	ds_bpermute_b32 v67, v165, v66
	s_waitcnt vmcnt(12)
	v_pk_add_f32 v[82:83], v[38:39], 1.0 op_sel_hi:[1,0]
	v_cmp_lt_i32_e32 vcc, v86, v87
	s_waitcnt vmcnt(11)
	v_pk_add_f32 v[44:45], v[44:45], 1.0 op_sel_hi:[1,0]
	s_waitcnt vmcnt(9)
	v_pk_add_f32 v[52:53], v[52:53], 1.0 op_sel_hi:[1,0]
	s_waitcnt lgkmcnt(0)
	v_add_f32_e32 v66, v66, v67
	ds_bpermute_b32 v67, v169, v66
	v_pk_add_f32 v[42:43], v[42:43], 1.0 op_sel_hi:[1,0]
	v_pk_add_f32 v[50:51], v[50:51], 1.0 op_sel_hi:[1,0]
	v_pk_add_f32 v[84:85], v[48:49], 1.0 op_sel_hi:[1,0]
	s_waitcnt vmcnt(5)
	v_pk_mul_f32 v[48:49], v[78:79], v[50:51]
	s_waitcnt lgkmcnt(0)
	v_add_f32_e32 v55, v66, v67
	ds_bpermute_b32 v66, v168, v55
	v_cndmask_b32_e32 v67, v35, v86, vcc
	v_lshlrev_b32_e32 v164, 2, v67
	v_pk_add_f32 v[86:87], v[46:47], 1.0 op_sel_hi:[1,0]
	v_pk_mul_f32 v[50:51], v[76:77], v[84:85]
	s_waitcnt lgkmcnt(0)
	v_add_f32_e32 v55, v55, v66
	ds_bpermute_b32 v73, v167, v55
	v_pk_add_f32 v[66:67], v[40:41], 1.0 op_sel_hi:[1,0]
	v_pk_mul_f32 v[40:41], v[62:63], v[42:43]
	v_pk_mul_f32 v[42:43], v[60:61], v[66:67]
	v_cmp_eq_u32_e64 s[8:9], 3, v1
	s_waitcnt lgkmcnt(0)
	v_add_f32_e32 v38, v55, v73
	ds_bpermute_b32 v39, v166, v38
	s_waitcnt lgkmcnt(0)
	v_add_f32_e32 v46, v38, v39
	ds_bpermute_b32 v47, v164, v46
	v_pk_mul_f32 v[38:39], v[64:65], v[44:45]
	v_pk_mul_f32 v[44:45], v[58:59], v[82:83]
	s_waitcnt lgkmcnt(0)
; #define GAS __attribute__((address_space(1)))
; #define LAS __attribute__((address_space(3)))
; __device__ __forceinline__ unsigned pk2(float lo, float hi) { return pg8::cvt_pk_bf16(lo, hi); }
; template <int LO, int HI> __global__ void __launch_bounds__(NWAVES * 64, 2) fox_fwd(Args args) {
;     ...
;             for (int j = 0; j < 4; ++j) { v[j] = *(const GAS f32x4*)(xr + P1COL(j)); s2 += (v[j][0] * v[j][0] + v[j][1] * v[j][1]) + (v[j][2] * v[j][2] + v[j][3] * v[j][3]); }
;             const float rstd = 1.0f / sqrtf(wave_sum(s2) * (1.0f / D) + EPS);
; #pragma unroll
;             for (int j = 0; j < 4; ++j) v[j] = v[j] * rstd * gm[j] + sh[j];
; #pragma unroll
;             for (int j = 0; j < 2; ++j) { v4u o; o.x = pk2(v[2 * j][0], v[2 * j][1]); o.y = pk2(v[2 * j][2], v[2 * j][3]); o.z = pk2(v[2 * j + 1][0], v[2 * j + 1][1]); o.w = pk2(v[2 * j + 1][2], v[2 * j + 1][3]);
;                 *(GAS v4u*)(HB + (size_t)m * D + 8 * lane + 512 * j) = o; }
;             float fl[8];
; #pragma unroll
;             for (int q = 0; q < 8; ++q) { float a = 0.f;
; #pragma unroll
;                 for (int j = 0; j < 4; ++j) { const f32x4 w = *(const LAS f32x4*)(wf + q * 1024 + P1COL(j)); a += (v[j][0] * w[0] + v[j][1] * w[1]) + (v[j][2] * w[2] + v[j][3] * w[3]); }
;                 fl[q] = wave_sum(a); }
	v_add_f32_e32 v46, v46, v47
	v_fmamk_f32 v46, v46, 0x3a800000, v69
	v_mul_f32_e32 v47, 0x4f800000, v46
	v_cmp_gt_f32_e32 vcc, s45, v46
	s_nop 1
	v_cndmask_b32_e32 v55, v46, v47, vcc
	v_sqrt_f32_e32 v58, v55
	v_pk_mul_f32 v[46:47], v[80:81], v[52:53]
	v_add_u32_e32 v52, -1, v58
	v_add_u32_e32 v53, 1, v58
	v_fma_f32 v59, -v52, v58, v55
	v_fma_f32 v60, -v53, v58, v55
	v_cmp_ge_f32_e64 s[4:5], 0, v59
	s_nop 1
	v_cndmask_b32_e64 v52, v58, v52, s[4:5]
	v_cmp_lt_f32_e64 s[4:5], 0, v60
	s_nop 1
	v_cndmask_b32_e64 v52, v52, v53, s[4:5]
	v_mul_f32_e32 v53, 0x37800000, v52
	v_cndmask_b32_e32 v52, v52, v53, vcc
	v_cmp_class_f32_e32 vcc, v55, v70
	s_nop 1
	v_cndmask_b32_e32 v55, v52, v55, vcc
	v_div_scale_f32 v58, s[4:5], v55, v55, 1.0
	v_rcp_f32_e32 v59, v58
	v_div_scale_f32 v60, vcc, 1.0, v55, 1.0
	v_pk_mul_f32 v[52:53], v[74:75], v[86:87]
	v_fma_f32 v61, -v58, v59, 1.0
	v_fmac_f32_e32 v59, v61, v59
	v_mul_f32_e32 v61, v60, v59
	v_fma_f32 v62, -v58, v61, v60
	v_fmac_f32_e32 v61, v62, v59
	v_fma_f32 v58, -v58, v61, v60
	v_div_fmas_f32 v58, v58, v59, v61
	v_div_fixup_f32 v64, v58, v55, 1.0
	v_pk_mul_f32 v[18:19], v[64:65], v[18:19] op_sel_hi:[0,1]
	v_pk_mul_f32 v[20:21], v[64:65], v[20:21] op_sel_hi:[0,1]
	s_waitcnt vmcnt(3)
	v_pk_fma_f32 v[60:61], v[42:43], v[20:21], v[4:5]
	v_pk_fma_f32 v[62:63], v[44:45], v[18:19], v[2:3]
	v_pk_mul_f32 v[18:19], v[64:65], v[30:31] op_sel_hi:[0,1]
	v_pk_mul_f32 v[20:21], v[64:65], v[32:33] op_sel_hi:[0,1]
	v_pk_mul_f32 v[58:59], v[64:65], v[26:27] op_sel_hi:[0,1]
	v_pk_mul_f32 v[26:27], v[64:65], v[28:29] op_sel_hi:[0,1]
	s_waitcnt vmcnt(0)
	v_pk_fma_f32 v[28:29], v[46:47], v[20:21], v[16:17]
	v_pk_fma_f32 v[30:31], v[48:49], v[18:19], v[14:15]
	v_pk_mul_f32 v[18:19], v[64:65], v[22:23] op_sel_hi:[0,1]
	v_pk_mul_f32 v[20:21], v[64:65], v[24:25] op_sel_hi:[0,1]
	v_pk_fma_f32 v[26:27], v[38:39], v[26:27], v[8:9]
	v_pk_fma_f32 v[58:59], v[40:41], v[58:59], v[6:7]
	v_pk_fma_f32 v[22:23], v[50:51], v[20:21], v[12:13]
	v_pk_fma_f32 v[24:25], v[52:53], v[18:19], v[10:11]
	v_lshl_add_u64 v[32:33], v[56:57], 0, s[34:35]
	v_cvt_pk_bf16_f32 v18, v58, v59
	v_cvt_pk_bf16_f32 v19, v26, v27
	v_cvt_pk_bf16_f32 v20, v62, v63
	v_cvt_pk_bf16_f32 v21, v60, v61
	global_store_dwordx4 v[32:33], v[18:21], off
	s_lshl_b64 s[4:5], s[36:37], 12
	s_add_u32 s4, s6, s4
	v_cvt_pk_bf16_f32 v18, v30, v31
	v_cvt_pk_bf16_f32 v19, v28, v29
	v_cvt_pk_bf16_f32 v20, v24, v25
	v_cvt_pk_bf16_f32 v21, v22, v23
	ds_read_b128 v[64:67], v72
	ds_read_b128 v[74:77], v72 offset:16
	global_store_dwordx4 v[32:33], v[18:21], off offset:1024
	ds_read_b128 v[18:21], v72 offset:12288
	s_addc_u32 s5, s7, s5
	s_waitcnt lgkmcnt(2)
	v_mul_f32_e32 v55, v59, v65
	v_fmac_f32_e32 v55, v58, v64
	v_mul_f32_e32 v64, v27, v67
	v_fmac_f32_e32 v64, v26, v66
	v_add_f32_e32 v55, v55, v64
	ds_read_b128 v[64:67], v72 offset:2048
	s_waitcnt lgkmcnt(2)
	v_mul_f32_e32 v73, v63, v75
	v_fmac_f32_e32 v73, v62, v74
	v_mul_f32_e32 v74, v61, v77
	v_fmac_f32_e32 v74, v60, v76
	v_add_f32_e32 v73, v73, v74
	ds_read_b128 v[74:77], v72 offset:2064
	s_waitcnt lgkmcnt(1)
	v_mul_f32_e32 v65, v31, v65
	v_fmac_f32_e32 v65, v30, v64
	v_mul_f32_e32 v64, v29, v67
	v_add_f32_e32 v55, 0, v55
	v_fmac_f32_e32 v64, v28, v66
	v_add_f32_e32 v55, v55, v73
	v_add_f32_e32 v64, v65, v64
	v_add_f32_e32 v55, v55, v64
	s_waitcnt lgkmcnt(0)
	v_mul_f32_e32 v64, v25, v75
	v_mul_f32_e32 v65, v23, v77
	v_fmac_f32_e32 v64, v24, v74
	v_fmac_f32_e32 v65, v22, v76
	v_add_f32_e32 v64, v64, v65
	v_add_f32_e32 v55, v55, v64
	ds_bpermute_b32 v64, v165, v55
	ds_read_b128 v[74:77], v72 offset:4112
	v_cmp_eq_u32_e64 s[6:7], 2, v1
	s_waitcnt lgkmcnt(1)
	v_add_f32_e32 v55, v55, v64
	ds_bpermute_b32 v64, v169, v55
	s_waitcnt lgkmcnt(1)
	v_mul_f32_e32 v75, v63, v75
	v_fmac_f32_e32 v75, v62, v74
	v_mul_f32_e32 v74, v61, v77
	v_fmac_f32_e32 v74, v60, v76
	s_waitcnt lgkmcnt(0)
	v_add_f32_e32 v55, v55, v64
	ds_read_b128 v[64:67], v72 offset:4096
	v_add_f32_e32 v74, v75, v74
	ds_bpermute_b32 v73, v168, v55
	s_waitcnt lgkmcnt(1)
	v_mul_f32_e32 v65, v59, v65
	v_fmac_f32_e32 v65, v58, v64
	v_mul_f32_e32 v64, v27, v67
	v_fmac_f32_e32 v64, v26, v66
	v_add_f32_e32 v64, v65, v64
	v_add_f32_e32 v78, 0, v64
	ds_read_b128 v[64:67], v72 offset:6144
	v_add_f32_e32 v78, v78, v74
	ds_read_b128 v[74:77], v72 offset:6160
	s_waitcnt lgkmcnt(2)
	v_add_f32_e32 v55, v55, v73
	ds_bpermute_b32 v73, v167, v55
	s_waitcnt lgkmcnt(2)
	v_mul_f32_e32 v65, v31, v65
	v_fmac_f32_e32 v65, v30, v64
	v_mul_f32_e32 v64, v29, v67
	v_fmac_f32_e32 v64, v28, v66
	v_add_f32_e32 v64, v65, v64
	s_waitcnt lgkmcnt(1)
	v_mul_f32_e32 v65, v25, v75
	v_mul_f32_e32 v66, v23, v77
	v_fmac_f32_e32 v65, v24, v74
	v_fmac_f32_e32 v66, v22, v76
	v_add_f32_e32 v64, v78, v64
	v_add_f32_e32 v65, v65, v66
	v_add_f32_e32 v64, v64, v65
	ds_bpermute_b32 v65, v165, v64
	s_waitcnt lgkmcnt(1)
	v_add_f32_e32 v55, v55, v73
	ds_bpermute_b32 v74, v166, v55
	v_lshlrev_b32_e32 v73, 3, v1
	s_waitcnt lgkmcnt(1)
	v_add_f32_e32 v75, v64, v65
	ds_bpermute_b32 v76, v169, v75
	ds_read_b128 v[64:67], v72 offset:8192
	s_waitcnt lgkmcnt(2)
	v_add_f32_e32 v55, v55, v74
	s_waitcnt lgkmcnt(1)
	v_add_f32_e32 v78, v75, v76
	ds_read_b128 v[74:77], v72 offset:8208
	s_waitcnt lgkmcnt(1)
	v_mul_f32_e32 v65, v59, v65
	v_fmac_f32_e32 v65, v58, v64
	v_mul_f32_e32 v64, v27, v67
	v_fmac_f32_e32 v64, v26, v66
	v_add_f32_e32 v64, v65, v64
	s_waitcnt lgkmcnt(0)
	v_mul_f32_e32 v75, v63, v75
	v_add_f32_e32 v80, 0, v64
	v_fmac_f32_e32 v75, v62, v74
	v_mul_f32_e32 v74, v61, v77
	ds_read_b128 v[64:67], v72 offset:10240
	v_fmac_f32_e32 v74, v60, v76
	v_add_f32_e32 v74, v75, v74
	v_add_f32_e32 v80, v80, v74
	ds_read_b128 v[74:77], v72 offset:10256
	s_waitcnt lgkmcnt(1)
; #define GAS __attribute__((address_space(1)))
; #define LAS __attribute__((address_space(3)))
; template <int LO, int HI> __global__ void __launch_bounds__(NWAVES * 64, 2) fox_fwd(Args args) {
;     ...
;         for (int r = 0; r < 16; ++r) { const int m = m0 + r;
;             const GAS float* xr = (const GAS float*)(x + (size_t)m * D);
;             f32x4 v[4]; float s2 = 0.f;
; #pragma unroll
;             for (int j = 0; j < 4; ++j) { v[j] = *(const GAS f32x4*)(xr + P1COL(j)); s2 += (v[j][0] * v[j][0] + v[j][1] * v[j][1]) + (v[j][2] * v[j][2] + v[j][3] * v[j][3]); }
;     ...
;             for (int q = 0; q < 8; ++q) { float a = 0.f;
; #pragma unroll
;                 for (int j = 0; j < 4; ++j) { const f32x4 w = *(const LAS f32x4*)(wf + q * 1024 + P1COL(j)); a += (v[j][0] * w[0] + v[j][1] * w[1]) + (v[j][2] * w[2] + v[j][3] * w[3]); }
;                 fl[q] = wave_sum(a); }
	v_mul_f32_e32 v65, v31, v65
	ds_bpermute_b32 v79, v168, v78
	v_fmac_f32_e32 v65, v30, v64
	v_mul_f32_e32 v64, v29, v67
	v_fmac_f32_e32 v64, v28, v66
	v_add_f32_e32 v64, v65, v64
	s_waitcnt lgkmcnt(1)
	v_mul_f32_e32 v65, v25, v75
	v_mul_f32_e32 v66, v23, v77
	v_fmac_f32_e32 v65, v24, v74
	v_fmac_f32_e32 v66, v22, v76
	v_add_f32_e32 v64, v80, v64
	v_add_f32_e32 v65, v65, v66
	v_add_f32_e32 v64, v64, v65
	s_waitcnt lgkmcnt(0)
	v_add_f32_e32 v67, v78, v79
	ds_bpermute_b32 v65, v165, v64
	ds_bpermute_b32 v66, v164, v55
	ds_bpermute_b32 v74, v167, v67
	s_waitcnt lgkmcnt(2)
	v_add_f32_e32 v32, v64, v65
	s_waitcnt lgkmcnt(1)
	v_add_f32_e32 v55, v55, v66
	s_waitcnt lgkmcnt(0)
	v_add_f32_e32 v74, v67, v74
	ds_read_b128 v[64:67], v72 offset:12304
	v_mul_f32_e32 v19, v59, v19
	v_fmac_f32_e32 v19, v58, v18
	v_mul_f32_e32 v18, v27, v21
	v_fmac_f32_e32 v18, v26, v20
	v_add_f32_e32 v18, v19, v18
	s_waitcnt lgkmcnt(0)
	v_mul_f32_e32 v65, v63, v65
	v_add_f32_e32 v76, 0, v18
	v_fmac_f32_e32 v65, v62, v64
	v_mul_f32_e32 v64, v61, v67
	ds_read_b128 v[18:21], v72 offset:14336
	v_fmac_f32_e32 v64, v60, v66
	v_add_f32_e32 v64, v65, v64
	v_add_f32_e32 v76, v76, v64
	ds_read_b128 v[64:67], v72 offset:14352
	s_waitcnt lgkmcnt(1)
	v_mul_f32_e32 v19, v31, v19
	v_fmac_f32_e32 v19, v30, v18
	v_mul_f32_e32 v18, v29, v21
	v_fmac_f32_e32 v18, v28, v20
	v_add_f32_e32 v18, v19, v18
	s_waitcnt lgkmcnt(0)
	v_mul_f32_e32 v19, v25, v65
	v_mul_f32_e32 v20, v23, v67
	v_fmac_f32_e32 v19, v24, v64
	v_fmac_f32_e32 v20, v22, v66
	v_add_f32_e32 v18, v76, v18
	v_add_f32_e32 v19, v19, v20
	v_add_f32_e32 v64, v18, v19
	ds_bpermute_b32 v75, v166, v74
	ds_bpermute_b32 v65, v165, v64
	ds_read_b128 v[18:21], v72 offset:16384
	ds_bpermute_b32 v33, v169, v32
	s_waitcnt lgkmcnt(3)
	v_add_f32_e32 v74, v74, v75
	s_waitcnt lgkmcnt(2)
	v_add_f32_e32 v75, v64, v65
	ds_read_b128 v[64:67], v72 offset:16400
	s_waitcnt lgkmcnt(2)
	v_mul_f32_e32 v19, v59, v19
	v_fmac_f32_e32 v19, v58, v18
	v_mul_f32_e32 v18, v27, v21
	v_fmac_f32_e32 v18, v26, v20
	v_add_f32_e32 v18, v19, v18
	s_waitcnt lgkmcnt(0)
	v_mul_f32_e32 v65, v63, v65
	v_add_f32_e32 v77, 0, v18
	v_fmac_f32_e32 v65, v62, v64
	v_mul_f32_e32 v64, v61, v67
	ds_read_b128 v[18:21], v72 offset:18432
	v_fmac_f32_e32 v64, v60, v66
	v_add_f32_e32 v64, v65, v64
	v_add_f32_e32 v32, v32, v33
	v_add_f32_e32 v77, v77, v64
	ds_read_b128 v[64:67], v72 offset:18448
	ds_bpermute_b32 v33, v168, v32
	s_waitcnt lgkmcnt(2)
	v_mul_f32_e32 v19, v31, v19
	v_fmac_f32_e32 v19, v30, v18
	v_mul_f32_e32 v18, v29, v21
	v_fmac_f32_e32 v18, v28, v20
	v_add_f32_e32 v18, v19, v18
	s_waitcnt lgkmcnt(1)
	v_mul_f32_e32 v19, v25, v65
	v_mul_f32_e32 v20, v23, v67
	s_waitcnt lgkmcnt(0)
	v_add_f32_e32 v32, v32, v33
	ds_bpermute_b32 v76, v169, v75
	v_fmac_f32_e32 v19, v24, v64
	v_fmac_f32_e32 v20, v22, v66
	ds_bpermute_b32 v33, v167, v32
	v_add_f32_e32 v18, v77, v18
	v_add_f32_e32 v19, v19, v20
	v_add_f32_e32 v18, v18, v19
	ds_bpermute_b32 v19, v165, v18
	s_waitcnt lgkmcnt(2)
	v_add_f32_e32 v21, v75, v76
	s_waitcnt lgkmcnt(1)
	v_add_f32_e32 v20, v32, v33
	ds_bpermute_b32 v32, v168, v21
	ds_bpermute_b32 v33, v166, v20
	s_waitcnt lgkmcnt(2)
	v_add_f32_e32 v18, v18, v19
	ds_bpermute_b32 v19, v169, v18
	ds_bpermute_b32 v64, v164, v74
	s_waitcnt lgkmcnt(3)
	v_add_f32_e32 v21, v21, v32
	ds_bpermute_b32 v32, v167, v21
	s_waitcnt lgkmcnt(3)
	v_add_f32_e32 v20, v20, v33
	s_waitcnt lgkmcnt(2)
	v_add_f32_e32 v18, v18, v19
	ds_bpermute_b32 v19, v168, v18
	ds_bpermute_b32 v33, v164, v20
	s_waitcnt lgkmcnt(2)
	v_add_f32_e32 v21, v21, v32
	ds_bpermute_b32 v32, v166, v21
	v_add_f32_e32 v74, v74, v64
	s_waitcnt lgkmcnt(2)
	v_add_f32_e32 v64, v18, v19
	ds_bpermute_b32 v65, v167, v64
	s_waitcnt lgkmcnt(2)
	v_add_f32_e32 v75, v20, v33
	s_waitcnt lgkmcnt(1)
	v_add_f32_e32 v32, v21, v32
	ds_read_b128 v[18:21], v72 offset:20480
	ds_bpermute_b32 v33, v164, v32
	s_waitcnt lgkmcnt(2)
	v_add_f32_e32 v76, v64, v65
	ds_read_b128 v[64:67], v72 offset:20496
	ds_bpermute_b32 v77, v166, v76
	s_waitcnt lgkmcnt(3)
	v_mul_f32_e32 v19, v59, v19
	v_fmac_f32_e32 v19, v58, v18
	v_mul_f32_e32 v18, v27, v21
	v_fmac_f32_e32 v18, v26, v20
	v_add_f32_e32 v18, v19, v18
	s_waitcnt lgkmcnt(1)
	v_mul_f32_e32 v65, v63, v65
	v_add_f32_e32 v78, 0, v18
	v_fmac_f32_e32 v65, v62, v64
	v_mul_f32_e32 v64, v61, v67
	ds_read_b128 v[18:21], v72 offset:22528
	v_fmac_f32_e32 v64, v60, v66
	v_add_f32_e32 v64, v65, v64
	v_add_f32_e32 v78, v78, v64
	ds_read_b128 v[64:67], v72 offset:22544
	s_waitcnt lgkmcnt(1)
	v_mul_f32_e32 v19, v31, v19
	v_fmac_f32_e32 v19, v30, v18
	v_mul_f32_e32 v18, v29, v21
	v_fmac_f32_e32 v18, v28, v20
	v_add_f32_e32 v18, v19, v18
	s_waitcnt lgkmcnt(0)
	v_mul_f32_e32 v19, v25, v65
	v_mul_f32_e32 v20, v23, v67
	v_fmac_f32_e32 v19, v24, v64
	v_fmac_f32_e32 v20, v22, v66
	v_add_f32_e32 v18, v78, v18
	v_add_f32_e32 v19, v19, v20
	v_add_f32_e32 v64, v18, v19
	ds_bpermute_b32 v65, v165, v64
	ds_read_b128 v[18:21], v72 offset:24576
	v_add_f32_e32 v92, v32, v33
	v_add_f32_e32 v93, v76, v77
	ds_bpermute_b32 v94, v164, v93
	s_waitcnt lgkmcnt(2)
	v_add_f32_e32 v95, v64, v65
	ds_read_b128 v[64:67], v72 offset:24592
	s_waitcnt lgkmcnt(2)
	v_pk_mul_f32 v[18:19], v[58:59], v[18:19]
	v_pk_mul_f32 v[20:21], v[26:27], v[20:21]
	ds_bpermute_b32 v96, v169, v95
	v_pk_mov_b32 v[32:33], v[18:19], v[20:21] op_sel:[1,0]
	v_mov_b32_e32 v19, v21
	v_pk_add_f32 v[18:19], v[32:33], v[18:19]
	s_waitcnt lgkmcnt(1)
	v_pk_mul_f32 v[64:65], v[62:63], v[64:65]
	v_add_f32_e32 v18, v18, v19
	v_add_f32_e32 v32, 0, v18
	ds_read_b128 v[18:21], v72 offset:26624
	ds_read_b128 v[76:79], v72 offset:26640
	global_load_dwordx4 v[80:83], v54, s[4:5] offset:16
	global_load_dwordx4 v[84:87], v54, s[4:5]
	v_pk_mul_f32 v[66:67], v[60:61], v[66:67]
	s_waitcnt lgkmcnt(0)
; #define GAS __attribute__((address_space(1)))
; #define LAS __attribute__((address_space(3)))
; __device__ __forceinline__ unsigned pk2(float lo, float hi) { return pg8::cvt_pk_bf16(lo, hi); }
; template <int LO, int HI> __global__ void __launch_bounds__(NWAVES * 64, 2) fox_fwd(Args args) {
;     ...
;             for (int j = 0; j < 4; ++j) { v[j] = *(const GAS f32x4*)(xr + P1COL(j)); s2 += (v[j][0] * v[j][0] + v[j][1] * v[j][1]) + (v[j][2] * v[j][2] + v[j][3] * v[j][3]); }
;             const float rstd = 1.0f / sqrtf(wave_sum(s2) * (1.0f / D) + EPS);
; #pragma unroll
;             for (int j = 0; j < 4; ++j) v[j] = v[j] * rstd * gm[j] + sh[j];
; #pragma unroll
;             for (int j = 0; j < 2; ++j) { v4u o; o.x = pk2(v[2 * j][0], v[2 * j][1]); o.y = pk2(v[2 * j][2], v[2 * j][3]); o.z = pk2(v[2 * j + 1][0], v[2 * j + 1][1]); o.w = pk2(v[2 * j + 1][2], v[2 * j + 1][3]);
;                 *(GAS v4u*)(HB + (size_t)m * D + 8 * lane + 512 * j) = o; }
;             float fl[8];
; #pragma unroll
;             for (int q = 0; q < 8; ++q) { float a = 0.f;
; #pragma unroll
;                 for (int j = 0; j < 4; ++j) { const f32x4 w = *(const LAS f32x4*)(wf + q * 1024 + P1COL(j)); a += (v[j][0] * w[0] + v[j][1] * w[1]) + (v[j][2] * w[2] + v[j][3] * w[3]); }
;                 fl[q] = wave_sum(a); }
;             float mine = fl[0];
; #pragma unroll
;             for (int q = 1; q < 8; ++q) mine = (lane == q) ? fl[q] : mine;
;             { const float z = mine + bfv; const float ls = fminf(z, 0.f) - log1pf(__expf(-fabsf(z)));
	v_mul_f32_e32 v33, v24, v76
	v_pk_mov_b32 v[88:89], v[64:65], v[66:67] op_sel:[1,0]
	v_mov_b32_e32 v65, v67
	v_pk_add_f32 v[64:65], v[88:89], v[64:65]
	v_mul_f32_e32 v66, v25, v77
	v_mul_f32_e32 v67, v22, v78
	v_mul_f32_e32 v97, v23, v79
	global_load_dwordx4 v[76:79], v54, s[4:5] offset:2048
	global_load_dwordx4 v[88:91], v54, s[4:5] offset:2064
	v_pk_add_f32 v[64:65], v[64:65], v[64:65] op_sel:[0,1] op_sel_hi:[1,0]
	v_cmp_eq_u32_e64 s[4:5], 1, v1
	v_mov_b32_e32 v65, v66
	v_pk_add_f32 v[32:33], v[32:33], v[64:65]
	v_mul_f32_e32 v64, v31, v19
	v_pk_fma_f32 v[18:19], v[30:31], v[18:19], v[64:65] op_sel_hi:[1,1,0]
	v_mul_f32_e32 v64, v29, v21
	v_pk_fma_f32 v[20:21], v[28:29], v[20:21], v[64:65] op_sel_hi:[1,1,0]
	v_mov_b32_e32 v19, v67
	v_mov_b32_e32 v21, v97
	v_pk_add_f32 v[64:65], v[18:19], v[20:21]
	ds_read_b128 v[18:21], v72 offset:28672
	v_pk_add_f32 v[32:33], v[32:33], v[64:65]
	ds_read_b128 v[64:67], v72 offset:28688
	v_add_f32_e32 v97, v32, v33
	ds_bpermute_b32 v98, v165, v97
	s_waitcnt lgkmcnt(2)
	v_pk_mul_f32 v[18:19], v[58:59], v[18:19]
	v_pk_mul_f32 v[20:21], v[26:27], v[20:21]
	s_waitcnt lgkmcnt(1)
	v_pk_mul_f32 v[32:33], v[62:63], v[64:65]
	v_pk_mov_b32 v[26:27], v[18:19], v[20:21] op_sel:[1,0]
	v_mov_b32_e32 v19, v21
	v_pk_add_f32 v[18:19], v[26:27], v[18:19]
	v_pk_mul_f32 v[58:59], v[60:61], v[66:67]
	v_add_f32_e32 v18, v18, v19
	v_add_f32_e32 v26, 0, v18
	ds_read_b128 v[18:21], v72 offset:30720
	ds_read_b128 v[62:65], v72 offset:30736
	v_pk_mov_b32 v[60:61], v[32:33], v[58:59] op_sel:[1,0]
	v_mov_b32_e32 v33, v59
	v_pk_add_f32 v[32:33], v[60:61], v[32:33]
	s_waitcnt lgkmcnt(0)
	v_mul_f32_e32 v27, v24, v62
	v_mul_f32_e32 v24, v25, v63
	v_mul_f32_e32 v25, v22, v64
	v_mul_f32_e32 v58, v23, v65
	v_pk_add_f32 v[22:23], v[32:33], v[32:33] op_sel:[0,1] op_sel_hi:[1,0]
	s_nop 0
	v_mov_b32_e32 v23, v24
	v_mul_f32_e32 v24, v31, v19
	v_pk_fma_f32 v[18:19], v[30:31], v[18:19], v[24:25] op_sel_hi:[1,1,0]
	v_mul_f32_e32 v24, v29, v21
	v_pk_fma_f32 v[20:21], v[28:29], v[20:21], v[24:25] op_sel_hi:[1,1,0]
	v_mov_b32_e32 v19, v25
	v_mov_b32_e32 v21, v58
	v_pk_add_f32 v[22:23], v[26:27], v[22:23]
	v_pk_add_f32 v[18:19], v[18:19], v[20:21]
	v_add_f32_e32 v20, v95, v96
	v_pk_add_f32 v[18:19], v[22:23], v[18:19]
	ds_bpermute_b32 v21, v168, v20
	v_add_f32_e32 v18, v18, v19
	ds_bpermute_b32 v19, v165, v18
	v_add_f32_e32 v22, v97, v98
	ds_bpermute_b32 v23, v169, v22
	s_waitcnt lgkmcnt(2)
	v_add_f32_e32 v20, v20, v21
	ds_bpermute_b32 v21, v167, v20
	s_waitcnt lgkmcnt(2)
	v_add_f32_e32 v18, v18, v19
	ds_bpermute_b32 v19, v169, v18
	s_waitcnt lgkmcnt(2)
	v_add_f32_e32 v22, v22, v23
	ds_bpermute_b32 v23, v168, v22
	s_waitcnt lgkmcnt(2)
	v_add_f32_e32 v20, v20, v21
	ds_bpermute_b32 v21, v166, v20
	s_waitcnt lgkmcnt(2)
	v_add_f32_e32 v18, v18, v19
	ds_bpermute_b32 v19, v168, v18
	s_waitcnt lgkmcnt(2)
	v_add_f32_e32 v22, v22, v23
	ds_bpermute_b32 v23, v167, v22
	s_waitcnt lgkmcnt(2)
	v_add_f32_e32 v26, v20, v21
	ds_bpermute_b32 v27, v164, v26
	s_waitcnt lgkmcnt(2)
	v_add_f32_e32 v18, v18, v19
	ds_bpermute_b32 v19, v167, v18
	s_waitcnt vmcnt(2)
	v_pk_mul_f32 v[20:21], v[84:85], v[84:85]
	s_waitcnt lgkmcnt(2)
	v_add_f32_e32 v28, v22, v23
	ds_bpermute_b32 v29, v166, v28
	s_waitcnt lgkmcnt(1)
	v_add_f32_e32 v30, v18, v19
	v_pk_mul_f32 v[18:19], v[86:87], v[86:87]
	ds_bpermute_b32 v31, v166, v30
	v_pk_mov_b32 v[22:23], v[20:21], v[18:19] op_sel:[1,0]
	v_mov_b32_e32 v21, v19
	v_pk_add_f32 v[18:19], v[22:23], v[20:21]
	v_pk_mul_f32 v[20:21], v[82:83], v[82:83]
	v_pk_mul_f32 v[22:23], v[80:81], v[80:81]
	v_pk_add_f32 v[18:19], v[18:19], v[18:19] op_sel:[0,1] op_sel_hi:[1,0]
	v_pk_mov_b32 v[24:25], v[22:23], v[20:21] op_sel:[1,0]
	v_mov_b32_e32 v23, v21
	v_pk_add_f32 v[20:21], v[24:25], v[22:23]
	s_waitcnt vmcnt(0)
	v_mul_f32_e32 v22, v88, v88
	v_mul_f32_e32 v23, v89, v89
	v_pk_add_f32 v[20:21], v[20:21], v[20:21] op_sel:[0,1] op_sel_hi:[1,0]
	v_mov_b32_e32 v19, v22
	v_mov_b32_e32 v21, v23
	v_pk_add_f32 v[18:19], v[18:19], v[20:21]
	v_mul_f32_e32 v20, v77, v77
	v_mul_f32_e32 v22, v79, v79
	v_mul_f32_e32 v24, v90, v90
	v_mul_f32_e32 v25, v91, v91
	v_pk_fma_f32 v[20:21], v[76:77], v[76:77], v[20:21] op_sel_hi:[1,1,0]
	v_pk_fma_f32 v[22:23], v[78:79], v[78:79], v[22:23] op_sel_hi:[1,1,0]
	v_mov_b32_e32 v21, v24
	v_mov_b32_e32 v23, v25
	v_pk_add_f32 v[20:21], v[20:21], v[22:23]
	s_waitcnt lgkmcnt(0)
	v_add_f32_e32 v22, v30, v31
	v_pk_add_f32 v[18:19], v[18:19], v[20:21]
	v_add_f32_e32 v20, v28, v29
	v_add_f32_e32 v18, v18, v19
	ds_bpermute_b32 v19, v165, v18
	ds_bpermute_b32 v21, v164, v20
	ds_bpermute_b32 v23, v164, v22
	v_add_f32_e32 v24, v93, v94
	v_add_f32_e32 v25, v26, v27
	s_waitcnt lgkmcnt(2)
	v_add_f32_e32 v18, v18, v19
	ds_bpermute_b32 v19, v169, v18
	s_waitcnt lgkmcnt(2)
	v_add_f32_e32 v20, v20, v21
	s_waitcnt lgkmcnt(1)
	v_add_f32_e32 v21, v22, v23
	v_cndmask_b32_e64 v22, v55, v74, s[4:5]
	v_cndmask_b32_e64 v22, v22, v75, s[6:7]
	s_waitcnt lgkmcnt(0)
	v_add_f32_e32 v18, v18, v19
	ds_bpermute_b32 v19, v168, v18
	v_cndmask_b32_e64 v22, v22, v92, s[8:9]
	v_cndmask_b32_e64 v22, v22, v24, s[10:11]
	v_cndmask_b32_e64 v22, v22, v25, s[12:13]
	v_cndmask_b32_e64 v20, v22, v20, s[14:15]
	s_waitcnt lgkmcnt(0)
	v_add_f32_e32 v18, v18, v19
	ds_bpermute_b32 v19, v167, v18
	v_cndmask_b32_e64 v20, v20, v21, s[16:17]
	v_add_f32_e32 v20, v71, v20
	v_min_f32_e32 v22, 0, v20
	v_mul_f32_e64 v20, |v20|, s29
	s_waitcnt lgkmcnt(0)
	v_add_f32_e32 v18, v18, v19
	ds_bpermute_b32 v19, v166, v18
	v_exp_f32_e32 v55, v20
	s_waitcnt lgkmcnt(0)
	v_add_f32_e32 v18, v18, v19
	ds_bpermute_b32 v19, v164, v18
	v_add_f32_e32 v92, 1.0, v55
	v_add_f32_e32 v23, -1.0, v92
	v_sub_f32_e32 v26, v23, v92
	v_add_f32_e32 v26, 1.0, v26
	s_waitcnt lgkmcnt(0)
; #define GAS __attribute__((address_space(1)))
; #define LAS __attribute__((address_space(3)))
; __device__ __forceinline__ unsigned pk2(float lo, float hi) { return pg8::cvt_pk_bf16(lo, hi); }
; template <int LO, int HI> __global__ void __launch_bounds__(NWAVES * 64, 2) fox_fwd(Args args) {
;     ...
;             for (int j = 0; j < 4; ++j) { v[j] = *(const GAS f32x4*)(xr + P1COL(j)); s2 += (v[j][0] * v[j][0] + v[j][1] * v[j][1]) + (v[j][2] * v[j][2] + v[j][3] * v[j][3]); }
;             const float rstd = 1.0f / sqrtf(wave_sum(s2) * (1.0f / D) + EPS);
; #pragma unroll
;             for (int j = 0; j < 4; ++j) v[j] = v[j] * rstd * gm[j] + sh[j];
; #pragma unroll
;             for (int j = 0; j < 2; ++j) { v4u o; o.x = pk2(v[2 * j][0], v[2 * j][1]); o.y = pk2(v[2 * j][2], v[2 * j][3]); o.z = pk2(v[2 * j + 1][0], v[2 * j + 1][1]); o.w = pk2(v[2 * j + 1][2], v[2 * j + 1][3]);
;                 *(GAS v4u*)(HB + (size_t)m * D + 8 * lane + 512 * j) = o; }
;             float fl[8];
; #pragma unroll
;             for (int q = 0; q < 8; ++q) { float a = 0.f;
; #pragma unroll
;                 for (int j = 0; j < 4; ++j) { const f32x4 w = *(const LAS f32x4*)(wf + q * 1024 + P1COL(j)); a += (v[j][0] * w[0] + v[j][1] * w[1]) + (v[j][2] * w[2] + v[j][3] * w[3]); }
;                 fl[q] = wave_sum(a); }
;             float mine = fl[0];
; #pragma unroll
;             for (int q = 1; q < 8; ++q) mine = (lane == q) ? fl[q] : mine;
;             { const float z = mine + bfv; const float ls = fminf(z, 0.f) - log1pf(__expf(-fabsf(z)));
	v_add_f32_e32 v18, v18, v19
	v_fmamk_f32 v18, v18, 0x3a800000, v69
	v_mul_f32_e32 v19, 0x4f800000, v18
	v_cmp_gt_f32_e32 vcc, s45, v18
	v_sub_f32_e32 v23, v55, v23
	v_add_f32_e32 v23, v23, v26
	v_cndmask_b32_e32 v18, v18, v19, vcc
	v_sqrt_f32_e32 v19, v18
	s_nop 0
	v_add_u32_e32 v20, -1, v19
	v_fma_f32 v21, -v20, v19, v18
	v_cmp_ge_f32_e64 s[20:21], 0, v21
	v_add_u32_e32 v21, 1, v19
	s_nop 0
	v_cndmask_b32_e64 v20, v19, v20, s[20:21]
	v_fma_f32 v19, -v21, v19, v18
	v_cmp_lt_f32_e64 s[20:21], 0, v19
	s_nop 1
	v_cndmask_b32_e64 v19, v20, v21, s[20:21]
	v_mul_f32_e32 v20, 0x37800000, v19
	v_cndmask_b32_e32 v19, v19, v20, vcc
	v_cmp_class_f32_e32 vcc, v18, v70
	s_nop 1
	v_cndmask_b32_e32 v18, v19, v18, vcc
	v_div_scale_f32 v19, s[20:21], v18, v18, 1.0
	v_rcp_f32_e32 v20, v19
	s_lshl_b64 s[20:21], s[36:37], 11
	s_mov_b32 s37, 0x3f2aaaab
	s_mov_b32 s36, 0x3f317218
	v_fma_f32 v21, -v19, v20, 1.0
	v_fmac_f32_e32 v20, v21, v20
	v_div_scale_f32 v21, vcc, 1.0, v18, 1.0
	v_mul_f32_e32 v24, v21, v20
	v_fma_f32 v25, -v19, v24, v21
	v_fmac_f32_e32 v24, v25, v20
	v_fma_f32 v19, -v19, v24, v21
	v_div_fmas_f32 v19, v19, v20, v24
	v_div_fixup_f32 v18, v19, v18, 1.0
	v_pk_mul_f32 v[20:21], v[18:19], v[84:85] op_sel_hi:[0,1]
	v_pk_mul_f32 v[24:25], v[18:19], v[86:87] op_sel_hi:[0,1]
	v_pk_fma_f32 v[64:65], v[40:41], v[20:21], v[6:7]
	v_pk_mul_f32 v[20:21], v[18:19], v[80:81] op_sel_hi:[0,1]
	v_pk_fma_f32 v[62:63], v[38:39], v[24:25], v[8:9]
	v_pk_mul_f32 v[24:25], v[18:19], v[82:83] op_sel_hi:[0,1]
	v_pk_fma_f32 v[66:67], v[44:45], v[20:21], v[2:3]
	v_pk_mul_f32 v[20:21], v[18:19], v[76:77] op_sel_hi:[0,1]
	v_pk_fma_f32 v[32:33], v[42:43], v[24:25], v[4:5]
	v_pk_mul_f32 v[24:25], v[18:19], v[78:79] op_sel_hi:[0,1]
	v_pk_fma_f32 v[30:31], v[48:49], v[20:21], v[14:15]
	v_pk_mul_f32 v[20:21], v[18:19], v[88:89] op_sel_hi:[0,1]
	v_pk_mul_f32 v[18:19], v[18:19], v[90:91] op_sel_hi:[0,1]
	v_pk_fma_f32 v[28:29], v[46:47], v[24:25], v[16:17]
	v_pk_fma_f32 v[58:59], v[50:51], v[18:19], v[12:13]
	v_pk_fma_f32 v[60:61], v[52:53], v[20:21], v[10:11]
	v_lshl_add_u64 v[24:25], v[56:57], 0, s[20:21]
	v_cvt_pk_bf16_f32 v18, v64, v65
	v_cvt_pk_bf16_f32 v19, v62, v63
	v_cvt_pk_bf16_f32 v20, v66, v67
	v_cvt_pk_bf16_f32 v21, v32, v33
	global_store_dwordx4 v[24:25], v[18:21], off
	s_mov_b32 s20, 0x3e9b6dac
	s_nop 0
	v_cvt_pk_bf16_f32 v18, v30, v31
	v_cvt_pk_bf16_f32 v19, v28, v29
	v_cvt_pk_bf16_f32 v20, v60, v61
	v_cvt_pk_bf16_f32 v21, v58, v59
	ds_read_b128 v[74:77], v72
	ds_read_b128 v[78:81], v72 offset:16
	s_waitcnt lgkmcnt(1)
	v_mul_f32_e32 v26, v65, v75
	v_mul_f32_e32 v27, v63, v77
	v_fmac_f32_e32 v26, v64, v74
	v_fmac_f32_e32 v27, v62, v76
	ds_read_b128 v[74:77], v72 offset:2048
	v_add_f32_e32 v26, v26, v27
	s_waitcnt lgkmcnt(1)
	v_mul_f32_e32 v27, v67, v79
	v_mul_f32_e32 v56, v33, v81
	v_fmac_f32_e32 v27, v66, v78
	v_fmac_f32_e32 v56, v32, v80
	ds_read_b128 v[78:81], v72 offset:2064
	v_add_f32_e32 v26, 0, v26
	v_add_f32_e32 v27, v27, v56
	v_add_f32_e32 v26, v26, v27
	s_waitcnt lgkmcnt(1)
	v_mul_f32_e32 v27, v31, v75
	v_mul_f32_e32 v56, v29, v77
	v_fmac_f32_e32 v27, v30, v74
	v_fmac_f32_e32 v56, v28, v76
	v_add_f32_e32 v27, v27, v56
	v_add_f32_e32 v26, v26, v27
	s_waitcnt lgkmcnt(0)
	v_mul_f32_e32 v27, v61, v79
	v_mul_f32_e32 v56, v59, v81
	v_fmac_f32_e32 v27, v60, v78
	v_fmac_f32_e32 v56, v58, v80
	v_add_f32_e32 v27, v27, v56
	v_add_f32_e32 v56, v26, v27
	ds_bpermute_b32 v57, v165, v56
	v_frexp_mant_f32_e32 v74, v92
	v_cmp_gt_f32_e32 vcc, s37, v74
	ds_read_b128 v[74:77], v72 offset:4096
	v_cvt_f64_f32_e32 v[26:27], v92
	s_waitcnt lgkmcnt(1)
	v_add_f32_e32 v57, v56, v57
	ds_bpermute_b32 v78, v169, v57
	v_frexp_exp_i32_f64_e32 v26, v[26:27]
	v_subbrev_co_u32_e32 v56, vcc, 0, v26, vcc
	v_sub_u32_e32 v27, 0, v56
	s_waitcnt lgkmcnt(0)
	v_add_f32_e32 v57, v57, v78
	ds_read_b128 v[78:81], v72 offset:4112
	v_mul_f32_e32 v26, v65, v75
	v_fmac_f32_e32 v26, v64, v74
	v_mul_f32_e32 v74, v63, v77
	v_fmac_f32_e32 v74, v62, v76
	v_add_f32_e32 v26, v26, v74
	s_waitcnt lgkmcnt(0)
	v_mul_f32_e32 v79, v67, v79
	ds_read_b128 v[74:77], v72 offset:6144
	v_fmac_f32_e32 v79, v66, v78
	v_mul_f32_e32 v78, v33, v81
	v_fmac_f32_e32 v78, v32, v80
	v_add_f32_e32 v26, 0, v26
	v_add_f32_e32 v78, v79, v78
	v_add_f32_e32 v26, v26, v78
	ds_read_b128 v[78:81], v72 offset:6160
	s_waitcnt lgkmcnt(1)
	v_mul_f32_e32 v75, v31, v75
	v_fmac_f32_e32 v75, v30, v74
	v_mul_f32_e32 v74, v29, v77
	v_fmac_f32_e32 v74, v28, v76
	v_add_f32_e32 v74, v75, v74
	v_add_f32_e32 v26, v26, v74
	s_waitcnt lgkmcnt(0)
	v_mul_f32_e32 v74, v61, v79
	v_mul_f32_e32 v75, v59, v81
	v_fmac_f32_e32 v74, v60, v78
	v_fmac_f32_e32 v75, v58, v80
	v_add_f32_e32 v74, v74, v75
	v_add_f32_e32 v78, v26, v74
	ds_bpermute_b32 v79, v165, v78
	ds_read_b128 v[74:77], v72 offset:8192
	ds_bpermute_b32 v82, v168, v57
	v_ldexp_f32 v26, v92, v27
	s_waitcnt lgkmcnt(2)
	v_add_f32_e32 v83, v78, v79
	ds_read_b128 v[78:81], v72 offset:8208
	s_waitcnt lgkmcnt(2)
	v_mul_f32_e32 v75, v65, v75
	v_fmac_f32_e32 v75, v64, v74
	v_mul_f32_e32 v74, v63, v77
	v_fmac_f32_e32 v74, v62, v76
	v_add_f32_e32 v74, v75, v74
	s_waitcnt lgkmcnt(0)
	v_mul_f32_e32 v79, v67, v79
	v_add_f32_e32 v85, 0, v74
	v_fmac_f32_e32 v79, v66, v78
	v_mul_f32_e32 v78, v33, v81
	ds_read_b128 v[74:77], v72 offset:10240
	v_fmac_f32_e32 v78, v32, v80
	v_add_f32_e32 v78, v79, v78
	v_add_f32_e32 v85, v85, v78
	ds_read_b128 v[78:81], v72 offset:10256
	s_waitcnt lgkmcnt(1)
	v_mul_f32_e32 v75, v31, v75
	v_fmac_f32_e32 v75, v30, v74
	v_mul_f32_e32 v74, v29, v77
	v_fmac_f32_e32 v74, v28, v76
	v_add_f32_e32 v57, v57, v82
	v_add_f32_e32 v74, v75, v74
	s_waitcnt lgkmcnt(0)
; #define LAS __attribute__((address_space(3)))
; template <int LO, int HI> __global__ void __launch_bounds__(NWAVES * 64, 2) fox_fwd(Args args) {
;     ...
;             for (int q = 0; q < 8; ++q) { float a = 0.f;
; #pragma unroll
;                 for (int j = 0; j < 4; ++j) { const f32x4 w = *(const LAS f32x4*)(wf + q * 1024 + P1COL(j)); a += (v[j][0] * w[0] + v[j][1] * w[1]) + (v[j][2] * w[2] + v[j][3] * w[3]); }
;                 fl[q] = wave_sum(a); }
	v_mul_f32_e32 v75, v61, v79
	v_mul_f32_e32 v76, v59, v81
	ds_bpermute_b32 v82, v167, v57
	v_fmac_f32_e32 v75, v60, v78
	v_fmac_f32_e32 v76, v58, v80
	v_add_f32_e32 v74, v85, v74
	v_add_f32_e32 v75, v75, v76
	v_add_f32_e32 v74, v74, v75
	ds_bpermute_b32 v84, v169, v83
	ds_bpermute_b32 v75, v165, v74
	s_waitcnt lgkmcnt(2)
	v_add_f32_e32 v57, v57, v82
	ds_bpermute_b32 v76, v166, v57
	s_waitcnt lgkmcnt(2)
	v_add_f32_e32 v77, v83, v84
	s_waitcnt lgkmcnt(1)
	v_add_f32_e32 v74, v74, v75
	ds_bpermute_b32 v78, v168, v77
	ds_bpermute_b32 v75, v169, v74
	s_waitcnt lgkmcnt(2)
	v_add_f32_e32 v57, v57, v76
	ds_bpermute_b32 v76, v164, v57
	s_waitcnt lgkmcnt(2)
	v_add_f32_e32 v78, v77, v78
	s_waitcnt lgkmcnt(1)
	v_add_f32_e32 v80, v74, v75
	ds_bpermute_b32 v79, v167, v78
	ds_bpermute_b32 v81, v168, v80
	s_waitcnt lgkmcnt(2)
	v_add_f32_e32 v57, v57, v76
	ds_read_b128 v[74:77], v72 offset:12288
	s_waitcnt lgkmcnt(2)
	v_add_f32_e32 v82, v78, v79
	s_waitcnt lgkmcnt(1)
	v_add_f32_e32 v84, v80, v81
	ds_read_b128 v[78:81], v72 offset:12304
	s_waitcnt lgkmcnt(1)
	v_mul_f32_e32 v75, v65, v75
	v_fmac_f32_e32 v75, v64, v74
	v_mul_f32_e32 v74, v63, v77
	v_fmac_f32_e32 v74, v62, v76
	v_add_f32_e32 v74, v75, v74
	s_waitcnt lgkmcnt(0)
	v_mul_f32_e32 v79, v67, v79
	v_add_f32_e32 v85, 0, v74
	v_fmac_f32_e32 v79, v66, v78
	v_mul_f32_e32 v78, v33, v81
	ds_read_b128 v[74:77], v72 offset:14336
	v_fmac_f32_e32 v78, v32, v80
	v_add_f32_e32 v78, v79, v78
	v_add_f32_e32 v85, v85, v78
	ds_read_b128 v[78:81], v72 offset:14352
	s_waitcnt lgkmcnt(1)
	v_mul_f32_e32 v75, v31, v75
	v_fmac_f32_e32 v75, v30, v74
	v_mul_f32_e32 v74, v29, v77
	v_fmac_f32_e32 v74, v28, v76
	v_add_f32_e32 v74, v75, v74
	s_waitcnt lgkmcnt(0)
	v_mul_f32_e32 v79, v61, v79
	v_add_f32_e32 v85, v85, v74
	v_fmac_f32_e32 v79, v60, v78
	v_mul_f32_e32 v78, v59, v81
	ds_read_b128 v[74:77], v72 offset:16384
	v_fmac_f32_e32 v78, v58, v80
	v_add_f32_e32 v78, v79, v78
	v_add_f32_e32 v85, v85, v78
	ds_read_b128 v[78:81], v72 offset:16400
	s_waitcnt lgkmcnt(1)
	v_mul_f32_e32 v75, v65, v75
	v_fmac_f32_e32 v75, v64, v74
	v_mul_f32_e32 v74, v63, v77
	v_fmac_f32_e32 v74, v62, v76
	v_add_f32_e32 v74, v75, v74
	s_waitcnt lgkmcnt(0)
	v_mul_f32_e32 v79, v67, v79
	v_add_f32_e32 v87, 0, v74
	v_fmac_f32_e32 v79, v66, v78
	v_mul_f32_e32 v78, v33, v81
	ds_read_b128 v[74:77], v72 offset:18432
	v_fmac_f32_e32 v78, v32, v80
	v_add_f32_e32 v78, v79, v78
	v_add_f32_e32 v87, v87, v78
	ds_read_b128 v[78:81], v72 offset:18448
	s_waitcnt lgkmcnt(1)
	v_mul_f32_e32 v75, v31, v75
	v_fmac_f32_e32 v75, v30, v74
	v_mul_f32_e32 v74, v29, v77
	v_fmac_f32_e32 v74, v28, v76
	v_add_f32_e32 v74, v75, v74
	s_waitcnt lgkmcnt(0)
	v_mul_f32_e32 v75, v61, v79
	v_mul_f32_e32 v76, v59, v81
	v_fmac_f32_e32 v75, v60, v78
	v_fmac_f32_e32 v76, v58, v80
	v_add_f32_e32 v74, v87, v74
	v_add_f32_e32 v75, v75, v76
	v_add_f32_e32 v74, v74, v75
	ds_bpermute_b32 v86, v165, v85
	ds_bpermute_b32 v75, v165, v74
	ds_bpermute_b32 v76, v167, v84
	ds_bpermute_b32 v83, v166, v82
	s_waitcnt lgkmcnt(3)
	v_add_f32_e32 v77, v85, v86
	s_waitcnt lgkmcnt(2)
	v_add_f32_e32 v74, v74, v75
	ds_bpermute_b32 v78, v169, v77
	ds_bpermute_b32 v75, v169, v74
	s_waitcnt lgkmcnt(3)
	v_add_f32_e32 v76, v84, v76
	ds_bpermute_b32 v80, v166, v76
	s_waitcnt lgkmcnt(3)
	v_add_f32_e32 v79, v82, v83
	s_waitcnt lgkmcnt(2)
	v_add_f32_e32 v77, v77, v78
	s_waitcnt lgkmcnt(1)
	v_add_f32_e32 v74, v74, v75
	ds_bpermute_b32 v78, v168, v77
	ds_bpermute_b32 v75, v168, v74
	ds_bpermute_b32 v81, v164, v79
	s_waitcnt lgkmcnt(3)
	v_add_f32_e32 v76, v76, v80
	ds_bpermute_b32 v82, v164, v76
	s_waitcnt lgkmcnt(3)
	v_add_f32_e32 v77, v77, v78
	s_waitcnt lgkmcnt(2)
	v_add_f32_e32 v75, v74, v75
	ds_bpermute_b32 v78, v167, v77
	ds_bpermute_b32 v80, v167, v75
	s_waitcnt lgkmcnt(3)
	v_add_f32_e32 v74, v79, v81
	s_waitcnt lgkmcnt(1)
	v_add_f32_e32 v77, v77, v78
	s_waitcnt lgkmcnt(0)
	v_add_f32_e32 v79, v75, v80
	ds_bpermute_b32 v78, v166, v77
	ds_bpermute_b32 v84, v166, v79
	v_add_f32_e32 v75, v76, v82
	ds_read_b128 v[80:83], v72 offset:20480
	s_waitcnt lgkmcnt(2)
	v_add_f32_e32 v76, v77, v78
	s_waitcnt lgkmcnt(1)
	v_add_f32_e32 v78, v79, v84
	ds_read_b128 v[84:87], v72 offset:20496
	s_waitcnt lgkmcnt(1)
	v_mul_f32_e32 v81, v65, v81
	v_fmac_f32_e32 v81, v64, v80
	v_mul_f32_e32 v80, v63, v83
	v_fmac_f32_e32 v80, v62, v82
	v_add_f32_e32 v80, v81, v80
	s_waitcnt lgkmcnt(0)
	v_mul_f32_e32 v85, v67, v85
	v_add_f32_e32 v88, 0, v80
	v_fmac_f32_e32 v85, v66, v84
	v_mul_f32_e32 v84, v33, v87
	ds_read_b128 v[80:83], v72 offset:22528
	v_fmac_f32_e32 v84, v32, v86
	v_add_f32_e32 v84, v85, v84
	v_add_f32_e32 v88, v88, v84
	ds_read_b128 v[84:87], v72 offset:22544
	s_waitcnt lgkmcnt(1)
	v_mul_f32_e32 v81, v31, v81
	v_fmac_f32_e32 v81, v30, v80
	v_mul_f32_e32 v80, v29, v83
	v_fmac_f32_e32 v80, v28, v82
	v_add_f32_e32 v80, v81, v80
	s_waitcnt lgkmcnt(0)
	v_mul_f32_e32 v81, v61, v85
	v_fmac_f32_e32 v81, v60, v84
	ds_read_b128 v[82:85], v72 offset:24576
	v_mul_f32_e32 v87, v59, v87
	v_fmac_f32_e32 v87, v58, v86
	v_add_f32_e32 v80, v88, v80
	v_add_f32_e32 v81, v81, v87
	ds_read_b128 v[86:89], v72 offset:24592
	s_waitcnt lgkmcnt(1)
	v_pk_mul_f32 v[82:83], v[64:65], v[82:83]
	v_pk_mul_f32 v[84:85], v[62:63], v[84:85]
	v_add_f32_e32 v80, v80, v81
	v_pk_mov_b32 v[90:91], v[82:83], v[84:85] op_sel:[1,0]
	v_mov_b32_e32 v83, v85
	v_pk_add_f32 v[82:83], v[90:91], v[82:83]
	s_waitcnt lgkmcnt(0)
	v_pk_mul_f32 v[86:87], v[66:67], v[86:87]
	v_add_f32_e32 v82, v82, v83
	v_add_f32_e32 v94, 0, v82
	ds_read_b128 v[82:85], v72 offset:26624
	ds_read_b128 v[90:93], v72 offset:26640
	v_pk_mul_f32 v[88:89], v[32:33], v[88:89]
	ds_bpermute_b32 v81, v165, v80
	v_pk_mov_b32 v[96:97], v[86:87], v[88:89] op_sel:[1,0]
	v_mov_b32_e32 v87, v89
	v_pk_add_f32 v[86:87], v[96:97], v[86:87]
	s_waitcnt lgkmcnt(1)
; #define LAS __attribute__((address_space(3)))
; template <int LO, int HI> __global__ void __launch_bounds__(NWAVES * 64, 2) fox_fwd(Args args) {
;     ...
;             for (int q = 0; q < 8; ++q) { float a = 0.f;
; #pragma unroll
;                 for (int j = 0; j < 4; ++j) { const f32x4 w = *(const LAS f32x4*)(wf + q * 1024 + P1COL(j)); a += (v[j][0] * w[0] + v[j][1] * w[1]) + (v[j][2] * w[2] + v[j][3] * w[3]); }
;                 fl[q] = wave_sum(a); }
;             float mine = fl[0];
; #pragma unroll
;             for (int q = 1; q < 8; ++q) mine = (lane == q) ? fl[q] : mine;
;             { const float z = mine + bfv; const float ls = fminf(z, 0.f) - log1pf(__expf(-fabsf(z)));
; #pragma unroll
;               for (int k = 0; k < 4; ++k)
; #pragma unroll
;                   for (int e = 0; e < 4; ++e) lsq[k][e] = (r == 4 * k + e) ? ls : lsq[k][e]; }
	v_mul_f32_e32 v88, v61, v91
	v_pk_add_f32 v[86:87], v[86:87], v[86:87] op_sel:[0,1] op_sel_hi:[1,0]
	v_mul_f32_e32 v95, v60, v90
	v_mov_b32_e32 v87, v88
	v_pk_add_f32 v[88:89], v[94:95], v[86:87]
	v_mul_f32_e32 v86, v31, v83
	v_pk_fma_f32 v[82:83], v[30:31], v[82:83], v[86:87] op_sel_hi:[1,1,0]
	v_mul_f32_e32 v86, v29, v85
	v_mul_f32_e32 v90, v58, v92
	v_mul_f32_e32 v91, v59, v93
	v_pk_fma_f32 v[84:85], v[28:29], v[84:85], v[86:87] op_sel_hi:[1,1,0]
	v_mov_b32_e32 v83, v90
	v_mov_b32_e32 v85, v91
	v_pk_add_f32 v[82:83], v[82:83], v[84:85]
	ds_read_b128 v[84:87], v72 offset:28672
	v_pk_add_f32 v[82:83], v[88:89], v[82:83]
	ds_read_b128 v[88:91], v72 offset:28688
	v_add_f32_e32 v82, v82, v83
	ds_bpermute_b32 v83, v165, v82
	s_waitcnt lgkmcnt(2)
	v_pk_mul_f32 v[64:65], v[64:65], v[84:85]
	v_pk_mul_f32 v[62:63], v[62:63], v[86:87]
	s_waitcnt lgkmcnt(1)
	v_pk_mul_f32 v[66:67], v[66:67], v[88:89]
	v_pk_mov_b32 v[84:85], v[64:65], v[62:63] op_sel:[1,0]
	v_mov_b32_e32 v65, v63
	v_pk_add_f32 v[62:63], v[84:85], v[64:65]
	v_pk_mul_f32 v[32:33], v[32:33], v[90:91]
	v_add_f32_e32 v62, v62, v63
	v_add_f32_e32 v92, 0, v62
	ds_read_b128 v[62:65], v72 offset:30720
	ds_read_b128 v[84:87], v72 offset:30736
	v_pk_mov_b32 v[88:89], v[66:67], v[32:33] op_sel:[1,0]
	v_mov_b32_e32 v67, v33
	v_pk_add_f32 v[32:33], v[88:89], v[66:67]
	ds_bpermute_b32 v77, v164, v76
	s_waitcnt lgkmcnt(1)
	v_mul_f32_e32 v93, v60, v84
	v_mul_f32_e32 v60, v61, v85
	v_mul_f32_e32 v61, v58, v86
	v_mul_f32_e32 v59, v59, v87
	v_mul_f32_e32 v58, v31, v63
	v_pk_fma_f32 v[30:31], v[30:31], v[62:63], v[58:59] op_sel_hi:[1,1,0]
	v_mul_f32_e32 v58, v29, v65
	v_pk_add_f32 v[32:33], v[32:33], v[32:33] op_sel:[0,1] op_sel_hi:[1,0]
	v_pk_fma_f32 v[28:29], v[28:29], v[64:65], v[58:59] op_sel_hi:[1,1,0]
	v_mov_b32_e32 v33, v60
	v_mov_b32_e32 v31, v61
	v_mov_b32_e32 v29, v59
	v_pk_add_f32 v[32:33], v[92:93], v[32:33]
	v_pk_add_f32 v[28:29], v[30:31], v[28:29]
	v_add_f32_e32 v30, v80, v81
	v_pk_add_f32 v[28:29], v[32:33], v[28:29]
	ds_bpermute_b32 v31, v169, v30
	v_add_f32_e32 v28, v28, v29
	ds_bpermute_b32 v29, v165, v28
	v_add_f32_e32 v32, v82, v83
	ds_bpermute_b32 v33, v169, v32
	s_waitcnt lgkmcnt(2)
	v_add_f32_e32 v30, v30, v31
	ds_bpermute_b32 v31, v168, v30
	s_waitcnt lgkmcnt(2)
	v_add_f32_e32 v28, v28, v29
	ds_bpermute_b32 v29, v169, v28
	s_waitcnt lgkmcnt(2)
	v_add_f32_e32 v32, v32, v33
	ds_bpermute_b32 v33, v168, v32
	s_waitcnt lgkmcnt(2)
	v_add_f32_e32 v30, v30, v31
	ds_bpermute_b32 v31, v167, v30
	s_waitcnt lgkmcnt(2)
	v_add_f32_e32 v28, v28, v29
	ds_bpermute_b32 v29, v168, v28
	s_waitcnt lgkmcnt(2)
	v_add_f32_e32 v32, v32, v33
	ds_bpermute_b32 v33, v167, v32
	s_waitcnt lgkmcnt(2)
	v_add_f32_e32 v30, v30, v31
	ds_bpermute_b32 v31, v166, v30
	s_waitcnt lgkmcnt(2)
	v_add_f32_e32 v28, v28, v29
	ds_bpermute_b32 v29, v167, v28
	s_waitcnt lgkmcnt(2)
	v_add_f32_e32 v32, v32, v33
	ds_bpermute_b32 v33, v166, v32
	ds_bpermute_b32 v79, v164, v78
	s_waitcnt lgkmcnt(3)
	v_add_f32_e32 v30, v30, v31
	s_waitcnt lgkmcnt(2)
	v_add_f32_e32 v28, v28, v29
	ds_bpermute_b32 v29, v166, v28
	ds_bpermute_b32 v31, v164, v30
	s_waitcnt lgkmcnt(3)
	v_add_f32_e32 v32, v32, v33
	ds_bpermute_b32 v33, v164, v32
	v_add_f32_e32 v58, v76, v77
	s_waitcnt lgkmcnt(2)
	v_add_f32_e32 v28, v28, v29
	ds_bpermute_b32 v29, v164, v28
	v_add_f32_e32 v59, v78, v79
	s_waitcnt lgkmcnt(2)
	v_add_f32_e32 v30, v30, v31
	s_waitcnt lgkmcnt(1)
	v_add_f32_e32 v31, v32, v33
	global_store_dwordx4 v[24:25], v[18:21], off offset:1024
	s_waitcnt lgkmcnt(0)
	v_add_f32_e32 v28, v28, v29
	v_cndmask_b32_e64 v29, v57, v74, s[4:5]
	v_cndmask_b32_e64 v29, v29, v75, s[6:7]
	v_cndmask_b32_e64 v29, v29, v58, s[8:9]
	v_cndmask_b32_e64 v29, v29, v59, s[10:11]
	v_cndmask_b32_e64 v29, v29, v30, s[12:13]
	v_cndmask_b32_e64 v29, v29, v31, s[14:15]
	v_cndmask_b32_e64 v28, v29, v28, s[16:17]
	v_add_f32_e32 v29, v71, v28
	v_mul_f32_e64 v28, |v29|, s29
	v_exp_f32_e32 v78, v28
	v_ldexp_f32 v28, v23, v27
	v_min_f32_e32 v23, 0, v29
	v_add_f32_e32 v20, 1.0, v78
	v_add_f32_e32 v18, -1.0, v20
	v_sub_f32_e32 v19, v18, v20
	v_add_f32_e32 v19, 1.0, v19
	v_sub_f32_e32 v18, v78, v18
	v_add_f32_e32 v21, v18, v19
	v_frexp_mant_f32_e32 v24, v20
	v_cvt_f64_f32_e32 v[18:19], v20
	v_frexp_exp_i32_f64_e32 v18, v[18:19]
	v_cmp_gt_f32_e32 vcc, s37, v24
	s_nop 1
	v_subbrev_co_u32_e32 v57, vcc, 0, v18, vcc
	v_sub_u32_e32 v18, 0, v57
	v_ldexp_f32 v27, v20, v18
	v_ldexp_f32 v29, v21, v18
	v_pk_add_f32 v[18:19], v[26:27], 1.0 op_sel_hi:[1,0]
	v_pk_add_f32 v[32:33], v[26:27], -1.0 op_sel_hi:[1,0]
	v_pk_add_f32 v[20:21], v[18:19], -1.0 op_sel_hi:[1,0]
	v_pk_add_f32 v[58:59], v[32:33], 1.0 op_sel_hi:[1,0]
	v_pk_add_f32 v[20:21], v[26:27], v[20:21] neg_lo:[0,1] neg_hi:[0,1]
	v_pk_add_f32 v[26:27], v[26:27], v[58:59] neg_lo:[0,1] neg_hi:[0,1]
	v_pk_add_f32 v[20:21], v[28:29], v[20:21]
	v_pk_add_f32 v[26:27], v[28:29], v[26:27]
	v_pk_add_f32 v[24:25], v[18:19], v[20:21]
	v_pk_add_f32 v[28:29], v[32:33], v[26:27]
	v_rcp_f32_e32 v30, v24
	v_rcp_f32_e32 v31, v25
	v_pk_add_f32 v[18:19], v[24:25], v[18:19] neg_lo:[0,1] neg_hi:[0,1]
	v_pk_add_f32 v[32:33], v[28:29], v[32:33] neg_lo:[0,1] neg_hi:[0,1]
	v_pk_add_f32 v[18:19], v[20:21], v[18:19] neg_lo:[0,1] neg_hi:[0,1]
	v_pk_mul_f32 v[20:21], v[28:29], v[30:31]
	v_pk_add_f32 v[26:27], v[26:27], v[32:33] neg_lo:[0,1] neg_hi:[0,1]
	v_pk_mul_f32 v[32:33], v[24:25], v[20:21]
	v_cmp_neq_f32_e32 vcc, s46, v55
	v_pk_fma_f32 v[58:59], v[20:21], v[24:25], v[32:33] neg_lo:[0,0,1] neg_hi:[0,0,1]
	s_nop 0
	v_pk_fma_f32 v[58:59], v[20:21], v[18:19], v[58:59]
	s_nop 0
	v_pk_add_f32 v[60:61], v[32:33], v[58:59]
	s_nop 0
	v_pk_add_f32 v[62:63], v[28:29], v[60:61] neg_lo:[0,1] neg_hi:[0,1]
; template <int LO, int HI> __global__ void __launch_bounds__(NWAVES * 64, 2) fox_fwd(Args args) {
;     ...
;             { const float z = mine + bfv; const float ls = fminf(z, 0.f) - log1pf(__expf(-fabsf(z)));
; #pragma unroll
;               for (int k = 0; k < 4; ++k)
; #pragma unroll
;                   for (int e = 0; e < 4; ++e) lsq[k][e] = (r == 4 * k + e) ? ls : lsq[k][e]; }
	v_pk_add_f32 v[32:33], v[60:61], v[32:33] neg_lo:[0,1] neg_hi:[0,1]
	v_pk_add_f32 v[28:29], v[28:29], v[62:63] neg_lo:[0,1] neg_hi:[0,1]
	s_nop 0
	v_pk_add_f32 v[28:29], v[28:29], v[60:61] neg_lo:[0,1] neg_hi:[0,1]
	s_nop 0
	v_pk_add_f32 v[26:27], v[26:27], v[28:29]
	v_pk_add_f32 v[28:29], v[32:33], v[58:59] neg_lo:[0,1] neg_hi:[0,1]
	s_nop 0
	v_pk_add_f32 v[26:27], v[28:29], v[26:27]
	s_nop 0
	v_pk_add_f32 v[28:29], v[62:63], v[26:27]
	s_nop 0
	v_pk_mul_f32 v[32:33], v[30:31], v[28:29]
	s_nop 0
	v_pk_mul_f32 v[58:59], v[24:25], v[32:33]
	s_nop 0
	v_pk_fma_f32 v[24:25], v[32:33], v[24:25], v[58:59] neg_lo:[0,0,1] neg_hi:[0,0,1]
	s_nop 0
	v_pk_fma_f32 v[18:19], v[32:33], v[18:19], v[24:25]
	v_pk_add_f32 v[24:25], v[62:63], v[28:29] neg_lo:[0,1] neg_hi:[0,1]
	s_nop 0
	v_pk_add_f32 v[24:25], v[26:27], v[24:25]
	v_pk_add_f32 v[26:27], v[58:59], v[18:19]
	s_nop 0
	v_pk_add_f32 v[60:61], v[28:29], v[26:27] neg_lo:[0,1] neg_hi:[0,1]
	v_pk_add_f32 v[58:59], v[26:27], v[58:59] neg_lo:[0,1] neg_hi:[0,1]
	v_pk_add_f32 v[28:29], v[28:29], v[60:61] neg_lo:[0,1] neg_hi:[0,1]
	v_pk_add_f32 v[18:19], v[58:59], v[18:19] neg_lo:[0,1] neg_hi:[0,1]
	v_pk_add_f32 v[26:27], v[28:29], v[26:27] neg_lo:[0,1] neg_hi:[0,1]
	s_nop 0
	v_pk_add_f32 v[24:25], v[24:25], v[26:27]
	s_nop 0
	v_pk_add_f32 v[18:19], v[18:19], v[24:25]
	v_pk_add_f32 v[24:25], v[20:21], v[32:33]
	v_pk_add_f32 v[18:19], v[60:61], v[18:19]
	v_pk_add_f32 v[20:21], v[24:25], v[20:21] neg_lo:[0,1] neg_hi:[0,1]
	v_pk_mul_f32 v[18:19], v[30:31], v[18:19]
	v_pk_add_f32 v[20:21], v[32:33], v[20:21] neg_lo:[0,1] neg_hi:[0,1]
	v_cvt_f32_i32_e32 v32, v56
	v_pk_add_f32 v[18:19], v[20:21], v[18:19]
	v_cvt_f32_i32_e32 v33, v57
	v_pk_add_f32 v[26:27], v[24:25], v[18:19]
	s_nop 0
	v_pk_add_f32 v[20:21], v[26:27], v[24:25] neg_lo:[0,1] neg_hi:[0,1]
	v_pk_mul_f32 v[28:29], v[26:27], v[26:27]
	v_pk_add_f32 v[18:19], v[18:19], v[20:21] neg_lo:[0,1] neg_hi:[0,1]
	v_mov_b32_e32 v20, 0x3ecc95a3
	v_pk_fma_f32 v[30:31], v[28:29], s[20:21], v[20:21] op_sel_hi:[1,0,0]
	s_mov_b32 s20, 0x3f2aaada
	v_ldexp_f32 v24, v26, 1
	v_pk_fma_f32 v[30:31], v[28:29], v[30:31], s[20:21] op_sel_hi:[1,1,0]
	v_ldexp_f32 v25, v27, 1
	v_pk_mul_f32 v[26:27], v[26:27], v[28:29]
	v_pk_mul_f32 v[28:29], v[32:33], s[36:37] op_sel_hi:[1,0]
	v_pk_mul_f32 v[26:27], v[26:27], v[30:31]
	v_pk_fma_f32 v[58:59], v[32:33], s[36:37], v[28:29] op_sel_hi:[1,0,1] neg_lo:[0,0,1] neg_hi:[0,0,1]
	v_pk_add_f32 v[30:31], v[24:25], v[26:27]
	s_mov_b32 s20, 0xb102e308
	v_pk_add_f32 v[24:25], v[30:31], v[24:25] neg_lo:[0,1] neg_hi:[0,1]
	v_ldexp_f32 v57, v19, 1
	v_pk_fma_f32 v[32:33], v[32:33], s[20:21], v[58:59] op_sel_hi:[1,0,1]
	v_pk_add_f32 v[24:25], v[26:27], v[24:25] neg_lo:[0,1] neg_hi:[0,1]
	v_ldexp_f32 v18, v18, 1
	v_mov_b32_e32 v26, v28
	v_mov_b32_e32 v27, v25
	v_mov_b32_e32 v56, v32
	v_mov_b32_e32 v19, v57
	v_pk_add_f32 v[26:27], v[26:27], v[56:57]
	v_pk_add_f32 v[56:57], v[18:19], v[24:25]
	v_mov_b32_e32 v25, v31
	v_mov_b32_e32 v19, v57
	v_pk_add_f32 v[58:59], v[28:29], v[32:33]
	v_pk_add_f32 v[18:19], v[18:19], v[24:25]
	v_pk_add_f32 v[24:25], v[30:31], v[56:57]
	v_mov_b32_e32 v74, v30
	v_pk_add_f32 v[60:61], v[58:59], v[24:25]
	v_mov_b32_e32 v66, v24
	v_mov_b32_e32 v67, v61
	v_mov_b32_e32 v75, v59
	v_pk_add_f32 v[66:67], v[66:67], v[74:75] neg_lo:[0,1] neg_hi:[0,1]
	v_mov_b32_e32 v62, v60
	v_mov_b32_e32 v63, v59
	v_mov_b32_e32 v64, v58
	v_mov_b32_e32 v65, v29
	v_mov_b32_e32 v74, v58
	v_mov_b32_e32 v75, v61
	v_mov_b32_e32 v29, v67
	v_pk_add_f32 v[62:63], v[62:63], v[64:65] neg_lo:[0,1] neg_hi:[0,1]
	v_mov_b32_e32 v64, v24
	v_mov_b32_e32 v65, v33
	v_pk_add_f32 v[28:29], v[74:75], v[28:29] neg_lo:[0,1] neg_hi:[0,1]
	v_pk_add_f32 v[64:65], v[64:65], v[62:63] neg_lo:[0,1] neg_hi:[0,1]
	v_mov_b32_e32 v74, v28
	v_mov_b32_e32 v75, v63
	v_mov_b32_e32 v76, v60
	v_mov_b32_e32 v77, v25
	v_mov_b32_e32 v63, v31
	v_pk_add_f32 v[74:75], v[32:33], v[74:75] neg_lo:[0,1] neg_hi:[0,1]
	v_pk_add_f32 v[62:63], v[76:77], v[62:63] neg_lo:[0,1] neg_hi:[0,1]
	v_mov_b32_e32 v33, v59
	v_pk_add_f32 v[26:27], v[26:27], v[62:63] neg_lo:[0,1] neg_hi:[0,1]
	v_pk_add_f32 v[28:29], v[32:33], v[28:29] neg_lo:[0,1] neg_hi:[0,1]
	v_pk_add_f32 v[18:19], v[18:19], v[66:67] neg_lo:[0,1] neg_hi:[0,1]
	v_pk_add_f32 v[24:25], v[24:25], v[30:31] neg_lo:[0,1] neg_hi:[0,1]
	v_pk_add_f32 v[30:31], v[18:19], v[28:29]
	v_mov_b32_e32 v29, v65
	v_mov_b32_e32 v19, v27
	v_pk_add_f32 v[32:33], v[64:65], v[26:27]
	v_pk_add_f32 v[18:19], v[28:29], v[18:19]
	v_mov_b32_e32 v26, v30
	v_pk_add_f32 v[18:19], v[18:19], v[74:75] neg_lo:[0,1] neg_hi:[0,1]
	v_mov_b32_e32 v27, v33
	v_pk_add_f32 v[24:25], v[56:57], v[24:25] neg_lo:[0,1] neg_hi:[0,1]
	v_pk_add_f32 v[26:27], v[26:27], v[18:19] neg_lo:[0,1] neg_hi:[0,1]
	v_pk_add_f32 v[18:19], v[24:25], v[18:19] neg_lo:[0,1] neg_hi:[0,1]
	v_pk_add_f32 v[26:27], v[28:29], v[26:27] neg_lo:[0,1] neg_hi:[0,1]
	v_pk_add_f32 v[24:25], v[32:33], v[30:31]
	v_pk_add_f32 v[18:19], v[18:19], v[26:27]
	v_pk_add_f32 v[26:27], v[60:61], v[24:25]
	v_mov_b32_e32 v64, 0x7f800000
	v_pk_add_f32 v[28:29], v[26:27], v[60:61] neg_lo:[0,1] neg_hi:[0,1]
	v_mov_b32_e32 v65, 0x7fc00000
	v_pk_add_f32 v[24:25], v[24:25], v[28:29] neg_lo:[0,1] neg_hi:[0,1]
	v_mov_b32_e32 v66, 0xff800000
	v_pk_add_f32 v[18:19], v[18:19], v[24:25]
	s_add_u32 s20, s26, s34
	v_pk_add_f32 v[18:19], v[26:27], v[18:19]
	s_addc_u32 s21, s27, s35
	v_cndmask_b32_e32 v18, v64, v18, vcc
	v_cmp_neq_f32_e32 vcc, s46, v78
	s_mov_b64 s[34:35], 0x2000
	v_mov_b32_e32 v58, 0x3f317218
	v_cndmask_b32_e32 v19, v64, v19, vcc
	v_cmp_ngt_f32_e32 vcc, -1.0, v78
	v_mov_b32_e32 v21, v37
	v_mov_b32_e32 v30, v37
	v_cndmask_b32_e32 v19, v65, v19, vcc
; #define GAS __attribute__((address_space(1)))
; #define LAS __attribute__((address_space(3)))
; __device__ __forceinline__ unsigned pk2(float lo, float hi) { return pg8::cvt_pk_bf16(lo, hi); }
; template <int LO, int HI> __global__ void __launch_bounds__(NWAVES * 64, 2) fox_fwd(Args args) {
;     ...
;         for (int r = 0; r < 16; ++r) { const int m = m0 + r;
;             const GAS float* xr = (const GAS float*)(x + (size_t)m * D);
;             f32x4 v[4]; float s2 = 0.f;
; #pragma unroll
;             for (int j = 0; j < 4; ++j) { v[j] = *(const GAS f32x4*)(xr + P1COL(j)); s2 += (v[j][0] * v[j][0] + v[j][1] * v[j][1]) + (v[j][2] * v[j][2] + v[j][3] * v[j][3]); }
;             const float rstd = 1.0f / sqrtf(wave_sum(s2) * (1.0f / D) + EPS);
; #pragma unroll
;             for (int j = 0; j < 4; ++j) v[j] = v[j] * rstd * gm[j] + sh[j];
; #pragma unroll
;             for (int j = 0; j < 2; ++j) { v4u o; o.x = pk2(v[2 * j][0], v[2 * j][1]); o.y = pk2(v[2 * j][2], v[2 * j][3]); o.z = pk2(v[2 * j + 1][0], v[2 * j + 1][1]); o.w = pk2(v[2 * j + 1][2], v[2 * j + 1][3]);
;                 *(GAS v4u*)(HB + (size_t)m * D + 8 * lane + 512 * j) = o; }
;             float fl[8];
; #pragma unroll
;             for (int q = 0; q < 8; ++q) { float a = 0.f;
; #pragma unroll
;                 for (int j = 0; j < 4; ++j) { const f32x4 w = *(const LAS f32x4*)(wf + q * 1024 + P1COL(j)); a += (v[j][0] * w[0] + v[j][1] * w[1]) + (v[j][2] * w[2] + v[j][3] * w[3]); }
;                 fl[q] = wave_sum(a); }
;             float mine = fl[0];
; #pragma unroll
;             for (int q = 1; q < 8; ++q) mine = (lane == q) ? fl[q] : mine;
;             { const float z = mine + bfv; const float ls = fminf(z, 0.f) - log1pf(__expf(-fabsf(z)));
; #pragma unroll
;               for (int k = 0; k < 4; ++k)
; #pragma unroll
;                   for (int e = 0; e < 4; ++e) lsq[k][e] = (r == 4 * k + e) ? ls : lsq[k][e]; }
	v_cmp_ngt_f32_e32 vcc, -1.0, v55
	v_mov_b32_e32 v31, v37
	v_mov_b32_e32 v32, v37
	v_cndmask_b32_e32 v18, v65, v18, vcc
	v_cmp_neq_f32_e32 vcc, -1.0, v55
	v_mov_b32_e32 v33, v37
	v_mov_b32_e32 v26, v37
	v_cndmask_b32_e32 v18, v66, v18, vcc
	v_cmp_neq_f32_e32 vcc, -1.0, v78
	v_mov_b32_e32 v27, v37
	v_mov_b32_e32 v28, v37
	v_cndmask_b32_e32 v19, v66, v19, vcc
	v_cmp_lt_f32_e64 vcc, |v78|, s47
	v_mov_b32_e32 v29, v37
	v_mov_b32_e32 v24, v37
	v_cndmask_b32_e32 v19, v19, v78, vcc
	v_cmp_lt_f32_e64 vcc, |v55|, s47
	v_mov_b32_e32 v25, v37
	s_nop 0
	v_cndmask_b32_e32 v18, v18, v55, vcc
	v_pk_add_f32 v[18:19], v[22:23], v[18:19] neg_lo:[0,1] neg_hi:[0,1]
	v_mov_b32_e32 v55, v37
	v_lshl_add_u64 v[22:23], s[20:21], 0, v[36:37]
	s_mov_b64 s[20:21], 0x2001400
	v_lshl_add_u64 v[54:55], s[30:31], 0, v[54:55]
	v_lshl_add_u64 v[56:57], v[22:23], 0, s[20:21]
	s_mov_b64 s[30:31], 0
	v_mov_b32_e32 v22, v37
	v_mov_b32_e32 v23, v37
	ds_read_b128 v[100:103], v72
	ds_read_b128 v[104:107], v72 offset:16
	ds_read_b128 v[108:111], v72 offset:2048
	ds_read_b128 v[112:115], v72 offset:2064
	ds_read_b128 v[116:119], v72 offset:4096
	ds_read_b128 v[120:123], v72 offset:4112
	ds_read_b128 v[124:127], v72 offset:6144
	ds_read_b128 v[128:131], v72 offset:6160
	ds_read_b128 v[132:135], v72 offset:8192
	ds_read_b128 v[136:139], v72 offset:8208
	ds_read_b128 v[140:143], v72 offset:10240
	ds_read_b128 v[144:147], v72 offset:10256
	s_waitcnt lgkmcnt(0)
	ds_read_b128 v[148:151], v72 offset:12288
	ds_read_b128 v[152:155], v72 offset:12304
	ds_read_b128 v[156:159], v72 offset:14336
	ds_read_b128 v[170:173], v72 offset:14352
	ds_read_b128 v[174:177], v72 offset:16384
	ds_read_b128 v[178:181], v72 offset:16400
	ds_read_b128 v[182:185], v72 offset:18432
	ds_read_b128 v[186:189], v72 offset:18448
	ds_read_b128 v[190:193], v72 offset:20480
	ds_read_b128 v[194:197], v72 offset:20496
	ds_read_b128 v[198:201], v72 offset:22528
	ds_read_b128 v[202:205], v72 offset:22544
	s_waitcnt lgkmcnt(0)
	ds_read_b128 v[206:209], v72 offset:24576
	ds_read_b128 v[210:213], v72 offset:24592
	ds_read_b128 v[226:229], v72 offset:26624
	ds_read_b128 v[230:233], v72 offset:26640
	ds_read_b128 v[234:237], v72 offset:28672
	ds_read_b128 v[238:241], v72 offset:28688
	ds_read_b128 v[242:245], v72 offset:30720
	ds_read_b128 v[246:249], v72 offset:30736
	s_waitcnt lgkmcnt(0)
	s_mov_b32 s52, m0
	s_mov_b64 s[56:57], 0x2000
	s_mov_b64 s[58:59], 16
	s_mov_b64 s[60:61], 0x800
	v_lshrrev_b32_e32 v224, 6, v0
	v_mbcnt_lo_u32_b32 v225, -1, 0
	v_mbcnt_hi_u32_b32 v225, -1, v225
	v_readfirstlane_b32 s50, v224
	v_lshlrev_b32_e32 v224, 4, v225
	s_lshl_b32 s50, s50, 12
	s_add_i32 s51, s50, 0x8000
	s_add_i32 s50, s50, 0x11000
	s_mov_b32 s53, 0
	v_mov_b32_e32 v160, s53
	v_mov_b32_e32 v161, 0
	v_lshl_add_u64 v[160:161], v[54:55], 0, v[160:161]
	v_lshl_add_u64 v[250:251], v[160:161], 0, s[56:57]
	v_lshl_add_u64 v[252:253], v[160:161], 0, s[34:35]
	v_lshl_add_u64 v[254:255], v[160:161], 0, s[38:39]
	v_lshl_add_u64 v[252:253], v[252:253], 0, s[58:59]
	v_lshl_add_u64 v[254:255], v[254:255], 0, s[58:59]
	v_lshl_add_u64 v[160:161], v[250:251], 0, s[60:61]
	s_mov_b32 m0, s50
	s_nop 0
	global_load_lds_dwordx4 v[250:251], off
	s_add_i32 m0, s50, 0x400
	s_nop 0
	global_load_lds_dwordx4 v[252:253], off
	s_add_i32 m0, s50, 0x800
	s_nop 0
	global_load_lds_dwordx4 v[254:255], off
	s_add_i32 m0, s50, 0xc00
	s_nop 0
	global_load_lds_dwordx4 v[160:161], off
	s_movk_i32 s53, 0x1000
	v_mov_b32_e32 v160, s53
	v_mov_b32_e32 v161, 0
	v_lshl_add_u64 v[160:161], v[54:55], 0, v[160:161]
	v_lshl_add_u64 v[250:251], v[160:161], 0, s[56:57]
	v_lshl_add_u64 v[252:253], v[160:161], 0, s[34:35]
	v_lshl_add_u64 v[254:255], v[160:161], 0, s[38:39]
	v_lshl_add_u64 v[252:253], v[252:253], 0, s[58:59]
	v_lshl_add_u64 v[254:255], v[254:255], 0, s[58:59]
	v_lshl_add_u64 v[160:161], v[250:251], 0, s[60:61]
	s_mov_b32 m0, s51
	s_nop 0
	global_load_lds_dwordx4 v[250:251], off
	s_add_i32 m0, s51, 0x400
	s_nop 0
	global_load_lds_dwordx4 v[252:253], off
	s_add_i32 m0, s51, 0x800
	s_nop 0
	global_load_lds_dwordx4 v[254:255], off
	s_add_i32 m0, s51, 0xc00
	s_nop 0
	global_load_lds_dwordx4 v[160:161], off
.LBB0_131:
	s_cmp_eq_u32 s30, 0
	s_cbranch_scc1 .Lp1w4
	s_cmp_eq_u32 s30, 0xd000
	s_cbranch_scc1 .Lp1w4
	s_cmp_eq_u32 s30, 0x1000
	s_cbranch_scc1 .Lp1w6
	s_waitcnt vmcnt(8)
	s_branch .Lp1wz
.Lp1w6:
	s_waitcnt vmcnt(6)
	s_branch .Lp1wz
.Lp1w4:
	s_waitcnt vmcnt(4)
.Lp1wz:
	s_barrier
	s_bitcmp1_b32 s30, 12
	s_cselect_b32 s54, s51, s50
	v_add_u32_e32 v225, s54, v224
	ds_read_b128 v[60:63], v225
	ds_read_b128 v[74:77], v225 offset:1024
	ds_read_b128 v[78:81], v225 offset:2048
	ds_read_b128 v[82:85], v225 offset:3072
	s_waitcnt lgkmcnt(0)
	s_cmp_gt_u32 s30, 0xb000
	s_cbranch_scc1 .Lp1dma_skip
	s_add_i32 s53, s30, 0x2000
	v_mov_b32_e32 v160, s53
	v_mov_b32_e32 v161, 0
	v_lshl_add_u64 v[160:161], v[54:55], 0, v[160:161]
	v_lshl_add_u64 v[250:251], v[160:161], 0, s[56:57]
	v_lshl_add_u64 v[252:253], v[160:161], 0, s[34:35]
	v_lshl_add_u64 v[254:255], v[160:161], 0, s[38:39]
	v_lshl_add_u64 v[252:253], v[252:253], 0, s[58:59]
	v_lshl_add_u64 v[254:255], v[254:255], 0, s[58:59]
	v_lshl_add_u64 v[160:161], v[250:251], 0, s[60:61]
	s_mov_b32 m0, s54
	s_nop 0
	global_load_lds_dwordx4 v[250:251], off
	s_add_i32 m0, s54, 0x400
	s_nop 0
	global_load_lds_dwordx4 v[252:253], off
	s_add_i32 m0, s54, 0x800
	s_nop 0
	global_load_lds_dwordx4 v[254:255], off
	s_add_i32 m0, s54, 0xc00
	s_nop 0
	global_load_lds_dwordx4 v[160:161], off
; #define GAS __attribute__((address_space(1)))
; #define LAS __attribute__((address_space(3)))
; __device__ __forceinline__ unsigned pk2(float lo, float hi) { return pg8::cvt_pk_bf16(lo, hi); }
; template <int LO, int HI> __global__ void __launch_bounds__(NWAVES * 64, 2) fox_fwd(Args args) {
;     ...
;             f32x4 v[4]; float s2 = 0.f;
; #pragma unroll
;             for (int j = 0; j < 4; ++j) { v[j] = *(const GAS f32x4*)(xr + P1COL(j)); s2 += (v[j][0] * v[j][0] + v[j][1] * v[j][1]) + (v[j][2] * v[j][2] + v[j][3] * v[j][3]); }
;             const float rstd = 1.0f / sqrtf(wave_sum(s2) * (1.0f / D) + EPS);
; #pragma unroll
;             for (int j = 0; j < 4; ++j) v[j] = v[j] * rstd * gm[j] + sh[j];
; #pragma unroll
;             for (int j = 0; j < 2; ++j) { v4u o; o.x = pk2(v[2 * j][0], v[2 * j][1]); o.y = pk2(v[2 * j][2], v[2 * j][3]); o.z = pk2(v[2 * j + 1][0], v[2 * j + 1][1]); o.w = pk2(v[2 * j + 1][2], v[2 * j + 1][3]);
;                 *(GAS v4u*)(HB + (size_t)m * D + 8 * lane + 512 * j) = o; }
;             float fl[8];
; #pragma unroll
;             for (int q = 0; q < 8; ++q) { float a = 0.f;
; #pragma unroll
;                 for (int j = 0; j < 4; ++j) { const f32x4 w = *(const LAS f32x4*)(wf + q * 1024 + P1COL(j)); a += (v[j][0] * w[0] + v[j][1] * w[1]) + (v[j][2] * w[2] + v[j][3] * w[3]); }
.Lp1dma_skip:
	s_cmp_eq_u32 s30, 0
	v_pk_mul_f32 v[86:87], v[62:63], v[62:63]
	v_pk_mul_f32 v[88:89], v[60:61], v[60:61]
	v_pk_mul_f32 v[90:91], v[76:77], v[76:77]
	v_pk_mul_f32 v[92:93], v[74:75], v[74:75]
	v_pk_mov_b32 v[96:97], v[88:89], v[86:87] op_sel:[1,0]
	v_mov_b32_e32 v89, v87
	v_pk_mov_b32 v[86:87], v[92:93], v[90:91] op_sel:[1,0]
	v_mov_b32_e32 v93, v91
	v_mul_f32_e32 v36, v83, v83
	v_mul_f32_e32 v94, v85, v85
	v_pk_add_f32 v[88:89], v[96:97], v[88:89]
	v_pk_add_f32 v[86:87], v[86:87], v[92:93]
	v_mul_f32_e32 v59, v78, v78
	v_mul_f32_e32 v67, v79, v79
	v_mul_f32_e32 v98, v80, v80
	v_mul_f32_e32 v99, v81, v81
	v_pk_fma_f32 v[90:91], v[82:83], v[82:83], v[36:37] op_sel_hi:[1,1,0]
	v_pk_fma_f32 v[94:95], v[84:85], v[84:85], v[94:95] op_sel_hi:[1,1,0]
	v_pk_add_f32 v[88:89], v[88:89], v[88:89] op_sel:[0,1] op_sel_hi:[1,0]
	v_pk_add_f32 v[86:87], v[86:87], v[86:87] op_sel:[0,1] op_sel_hi:[1,0]
	v_mov_b32_e32 v91, v98
	v_mov_b32_e32 v95, v99
	v_mov_b32_e32 v89, v59
	v_mov_b32_e32 v87, v67
	v_pk_add_f32 v[90:91], v[90:91], v[94:95]
	v_pk_add_f32 v[86:87], v[88:89], v[86:87]
	s_nop 0
	v_pk_add_f32 v[86:87], v[86:87], v[90:91]
	s_nop 0
	v_add_f32_e32 v36, v86, v87
	s_waitcnt lgkmcnt(0)
	s_nop 1
	v_add_f32_dpp v59, v36, v36 quad_perm:[1,0,3,2] row_mask:0xf bank_mask:0xf
	s_nop 1
	v_add_f32_dpp v36, v59, v59 quad_perm:[2,3,0,1] row_mask:0xf bank_mask:0xf
	s_nop 1
	v_add_f32_dpp v59, v36, v36 row_half_mirror row_mask:0xf bank_mask:0xf
	s_nop 1
	v_add_f32_dpp v36, v59, v59 row_mirror row_mask:0xf bank_mask:0xf
	v_mov_b32_e32 v59, v36
	s_nop 1
	v_permlane16_swap_b32_e32 v59, v36
	v_add_f32_e32 v59, v59, v36
	v_mov_b32_e32 v36, v59
	s_nop 1
	v_permlane32_swap_b32_e32 v36, v59
	v_add_f32_e32 v36, v36, v59
	v_fmamk_f32 v36, v36, 0x3a800000, v69
	v_mul_f32_e32 v59, 0x4f800000, v36
	v_cmp_gt_f32_e32 vcc, s45, v36
	s_nop 1
	v_cndmask_b32_e32 v36, v36, v59, vcc
	v_sqrt_f32_e32 v59, v36
	s_nop 0
	v_add_u32_e32 v67, -1, v59
	v_add_u32_e32 v86, 1, v59
	v_fma_f32 v87, -v67, v59, v36
	v_fma_f32 v88, -v86, v59, v36
	v_cmp_ge_f32_e64 s[20:21], 0, v87
	s_nop 1
	v_cndmask_b32_e64 v59, v59, v67, s[20:21]
	v_cmp_lt_f32_e64 s[20:21], 0, v88
	s_nop 1
	v_cndmask_b32_e64 v59, v59, v86, s[20:21]
	v_mul_f32_e32 v67, 0x37800000, v59
	v_cndmask_b32_e32 v59, v59, v67, vcc
	v_cmp_class_f32_e32 vcc, v36, v70
	s_nop 1
	v_cndmask_b32_e32 v36, v59, v36, vcc
	v_div_scale_f32 v59, s[20:21], v36, v36, 1.0
	v_rcp_f32_e32 v86, v59
	v_div_scale_f32 v67, vcc, 1.0, v36, 1.0
	v_fma_f32 v87, -v59, v86, 1.0
	v_fmac_f32_e32 v86, v87, v86
	v_mul_f32_e32 v87, v67, v86
	v_fma_f32 v88, -v59, v87, v67
	v_fmac_f32_e32 v87, v88, v86
	v_fma_f32 v59, -v59, v87, v67
	v_div_fmas_f32 v59, v59, v86, v87
	v_div_fixup_f32 v36, v59, v36, 1.0
	v_pk_mul_f32 v[60:61], v[36:37], v[60:61] op_sel_hi:[0,1]
	v_pk_mul_f32 v[62:63], v[36:37], v[62:63] op_sel_hi:[0,1]
	v_pk_mul_f32 v[74:75], v[36:37], v[74:75] op_sel_hi:[0,1]
	v_pk_mul_f32 v[76:77], v[36:37], v[76:77] op_sel_hi:[0,1]
	v_pk_mul_f32 v[82:83], v[36:37], v[82:83] op_sel_hi:[0,1]
	v_pk_mul_f32 v[84:85], v[36:37], v[84:85] op_sel_hi:[0,1]
	v_pk_mul_f32 v[78:79], v[36:37], v[78:79] op_sel_hi:[0,1]
	v_pk_mul_f32 v[80:81], v[36:37], v[80:81] op_sel_hi:[0,1]
	v_pk_fma_f32 v[162:163], v[38:39], v[62:63], v[8:9]
	v_pk_fma_f32 v[214:215], v[40:41], v[60:61], v[6:7]
	v_pk_fma_f32 v[216:217], v[42:43], v[76:77], v[4:5]
	v_pk_fma_f32 v[218:219], v[44:45], v[74:75], v[2:3]
	v_cvt_pk_bf16_f32 v74, v214, v215
	v_cvt_pk_bf16_f32 v75, v162, v163
	v_pk_fma_f32 v[60:61], v[46:47], v[84:85], v[16:17]
	v_cvt_pk_bf16_f32 v76, v218, v219
	v_cvt_pk_bf16_f32 v77, v216, v217
	v_pk_fma_f32 v[62:63], v[48:49], v[82:83], v[14:15]
	v_pk_fma_f32 v[220:221], v[50:51], v[80:81], v[12:13]
	v_pk_fma_f32 v[222:223], v[52:53], v[78:79], v[10:11]
	global_store_dwordx4 v[56:57], v[74:77], off offset:-1024
	s_nop 1
	v_cvt_pk_bf16_f32 v74, v62, v63
	v_cvt_pk_bf16_f32 v75, v60, v61
	v_cvt_pk_bf16_f32 v76, v222, v223
	v_cvt_pk_bf16_f32 v77, v220, v221
	s_nop 0
	global_store_dwordx4 v[56:57], v[74:77], off
	v_mul_f32_e32 v36, v214, v100
	v_mul_f32_e32 v59, v214, v116
	v_mul_f32_e32 v67, v214, v132
	v_mul_f32_e32 v74, v214, v148
	v_mul_f32_e32 v75, v214, v174
	v_mul_f32_e32 v76, v214, v190
	v_mul_f32_e32 v77, v214, v206
	v_mul_f32_e32 v250, v214, v234
	v_fmac_f32_e32 v36, v215, v101
	v_fmac_f32_e32 v59, v215, v117
	v_fmac_f32_e32 v67, v215, v133
	v_fmac_f32_e32 v74, v215, v149
	v_fmac_f32_e32 v75, v215, v175
	v_fmac_f32_e32 v76, v215, v191
	v_fmac_f32_e32 v77, v215, v207
	v_fmac_f32_e32 v250, v215, v235
	v_fmac_f32_e32 v36, v162, v102
	v_fmac_f32_e32 v59, v162, v118
	v_fmac_f32_e32 v67, v162, v134
	v_fmac_f32_e32 v74, v162, v150
	v_fmac_f32_e32 v75, v162, v176
	v_fmac_f32_e32 v76, v162, v192
	v_fmac_f32_e32 v77, v162, v208
	v_fmac_f32_e32 v250, v162, v236
	v_fmac_f32_e32 v36, v163, v103
	v_fmac_f32_e32 v59, v163, v119
	v_fmac_f32_e32 v67, v163, v135
	v_fmac_f32_e32 v74, v163, v151
	v_fmac_f32_e32 v75, v163, v177
	v_fmac_f32_e32 v76, v163, v193
	v_fmac_f32_e32 v77, v163, v209
	v_fmac_f32_e32 v250, v163, v237
	v_fmac_f32_e32 v36, v218, v104
	v_fmac_f32_e32 v59, v218, v120
	v_fmac_f32_e32 v67, v218, v136
	v_fmac_f32_e32 v74, v218, v152
	v_fmac_f32_e32 v75, v218, v178
	v_fmac_f32_e32 v76, v218, v194
	v_fmac_f32_e32 v77, v218, v210
	v_fmac_f32_e32 v250, v218, v238
	v_fmac_f32_e32 v36, v219, v105
	v_fmac_f32_e32 v59, v219, v121
	v_fmac_f32_e32 v67, v219, v137
	v_fmac_f32_e32 v74, v219, v153
	v_fmac_f32_e32 v75, v219, v179
	v_fmac_f32_e32 v76, v219, v195
	v_fmac_f32_e32 v77, v219, v211
	v_fmac_f32_e32 v250, v219, v239
	v_fmac_f32_e32 v36, v216, v106
	v_fmac_f32_e32 v59, v216, v122
; #define LAS __attribute__((address_space(3)))
; template <int LO, int HI> __global__ void __launch_bounds__(NWAVES * 64, 2) fox_fwd(Args args) {
;     ...
;             for (int q = 0; q < 8; ++q) { float a = 0.f;
; #pragma unroll
;                 for (int j = 0; j < 4; ++j) { const f32x4 w = *(const LAS f32x4*)(wf + q * 1024 + P1COL(j)); a += (v[j][0] * w[0] + v[j][1] * w[1]) + (v[j][2] * w[2] + v[j][3] * w[3]); }
;                 fl[q] = wave_sum(a); }
	v_fmac_f32_e32 v67, v216, v138
	v_fmac_f32_e32 v74, v216, v154
	v_fmac_f32_e32 v75, v216, v180
	v_fmac_f32_e32 v76, v216, v196
	v_fmac_f32_e32 v77, v216, v212
	v_fmac_f32_e32 v250, v216, v240
	v_fmac_f32_e32 v36, v217, v107
	v_fmac_f32_e32 v59, v217, v123
	v_fmac_f32_e32 v67, v217, v139
	v_fmac_f32_e32 v74, v217, v155
	v_fmac_f32_e32 v75, v217, v181
	v_fmac_f32_e32 v76, v217, v197
	v_fmac_f32_e32 v77, v217, v213
	v_fmac_f32_e32 v250, v217, v241
	v_fmac_f32_e32 v36, v62, v108
	v_fmac_f32_e32 v59, v62, v124
	v_fmac_f32_e32 v67, v62, v140
	v_fmac_f32_e32 v74, v62, v156
	v_fmac_f32_e32 v75, v62, v182
	v_fmac_f32_e32 v76, v62, v198
	v_fmac_f32_e32 v77, v62, v226
	v_fmac_f32_e32 v250, v62, v242
	v_fmac_f32_e32 v36, v63, v109
	v_fmac_f32_e32 v59, v63, v125
	v_fmac_f32_e32 v67, v63, v141
	v_fmac_f32_e32 v74, v63, v157
	v_fmac_f32_e32 v75, v63, v183
	v_fmac_f32_e32 v76, v63, v199
	v_fmac_f32_e32 v77, v63, v227
	v_fmac_f32_e32 v250, v63, v243
	v_fmac_f32_e32 v36, v60, v110
	v_fmac_f32_e32 v59, v60, v126
	v_fmac_f32_e32 v67, v60, v142
	v_fmac_f32_e32 v74, v60, v158
	v_fmac_f32_e32 v75, v60, v184
	v_fmac_f32_e32 v76, v60, v200
	v_fmac_f32_e32 v77, v60, v228
	v_fmac_f32_e32 v250, v60, v244
	v_fmac_f32_e32 v36, v61, v111
	v_fmac_f32_e32 v59, v61, v127
	v_fmac_f32_e32 v67, v61, v143
	v_fmac_f32_e32 v74, v61, v159
	v_fmac_f32_e32 v75, v61, v185
	v_fmac_f32_e32 v76, v61, v201
	v_fmac_f32_e32 v77, v61, v229
	v_fmac_f32_e32 v250, v61, v245
	v_fmac_f32_e32 v36, v222, v112
	v_fmac_f32_e32 v59, v222, v128
	v_fmac_f32_e32 v67, v222, v144
	v_fmac_f32_e32 v74, v222, v170
	v_fmac_f32_e32 v75, v222, v186
	v_fmac_f32_e32 v76, v222, v202
	v_fmac_f32_e32 v77, v222, v230
	v_fmac_f32_e32 v250, v222, v246
	v_fmac_f32_e32 v36, v223, v113
	v_fmac_f32_e32 v59, v223, v129
	v_fmac_f32_e32 v67, v223, v145
	v_fmac_f32_e32 v74, v223, v171
	v_fmac_f32_e32 v75, v223, v187
	v_fmac_f32_e32 v76, v223, v203
	v_fmac_f32_e32 v77, v223, v231
	v_fmac_f32_e32 v250, v223, v247
	v_fmac_f32_e32 v36, v220, v114
	v_fmac_f32_e32 v59, v220, v130
	v_fmac_f32_e32 v67, v220, v146
	v_fmac_f32_e32 v74, v220, v172
	v_fmac_f32_e32 v75, v220, v188
	v_fmac_f32_e32 v76, v220, v204
	v_fmac_f32_e32 v77, v220, v232
	v_fmac_f32_e32 v250, v220, v248
	v_fmac_f32_e32 v36, v221, v115
	v_fmac_f32_e32 v59, v221, v131
	v_fmac_f32_e32 v67, v221, v147
	v_fmac_f32_e32 v74, v221, v173
	v_fmac_f32_e32 v75, v221, v189
	v_fmac_f32_e32 v76, v221, v205
	v_fmac_f32_e32 v77, v221, v233
	v_fmac_f32_e32 v250, v221, v249
	v_mov_b32_e32 v60, v250
	v_mov_b32_e32 v61, 0
	s_waitcnt lgkmcnt(0)
	v_add_f32_e32 v60, v60, v61
	v_add_f32_dpp v62, v36, v36 quad_perm:[1,0,3,2] row_mask:0xf bank_mask:0xf
	v_add_f32_dpp v63, v59, v59 quad_perm:[1,0,3,2] row_mask:0xf bank_mask:0xf
	v_add_f32_dpp v78, v67, v67 quad_perm:[1,0,3,2] row_mask:0xf bank_mask:0xf
	v_add_f32_dpp v79, v74, v74 quad_perm:[1,0,3,2] row_mask:0xf bank_mask:0xf
	v_add_f32_dpp v80, v75, v75 quad_perm:[1,0,3,2] row_mask:0xf bank_mask:0xf
	v_add_f32_dpp v81, v76, v76 quad_perm:[1,0,3,2] row_mask:0xf bank_mask:0xf
	v_add_f32_dpp v82, v77, v77 quad_perm:[1,0,3,2] row_mask:0xf bank_mask:0xf
	v_add_f32_dpp v61, v60, v60 quad_perm:[1,0,3,2] row_mask:0xf bank_mask:0xf
	v_add_f32_dpp v36, v62, v62 quad_perm:[2,3,0,1] row_mask:0xf bank_mask:0xf
	v_add_f32_dpp v59, v63, v63 quad_perm:[2,3,0,1] row_mask:0xf bank_mask:0xf
	v_add_f32_dpp v67, v78, v78 quad_perm:[2,3,0,1] row_mask:0xf bank_mask:0xf
	v_add_f32_dpp v74, v79, v79 quad_perm:[2,3,0,1] row_mask:0xf bank_mask:0xf
	v_add_f32_dpp v75, v80, v80 quad_perm:[2,3,0,1] row_mask:0xf bank_mask:0xf
	v_add_f32_dpp v76, v81, v81 quad_perm:[2,3,0,1] row_mask:0xf bank_mask:0xf
	v_add_f32_dpp v77, v82, v82 quad_perm:[2,3,0,1] row_mask:0xf bank_mask:0xf
	v_add_f32_dpp v60, v61, v61 quad_perm:[2,3,0,1] row_mask:0xf bank_mask:0xf
	v_add_f32_dpp v62, v36, v36 row_half_mirror row_mask:0xf bank_mask:0xf
	v_add_f32_dpp v63, v59, v59 row_half_mirror row_mask:0xf bank_mask:0xf
	v_add_f32_dpp v78, v67, v67 row_half_mirror row_mask:0xf bank_mask:0xf
	v_add_f32_dpp v79, v74, v74 row_half_mirror row_mask:0xf bank_mask:0xf
	v_add_f32_dpp v80, v75, v75 row_half_mirror row_mask:0xf bank_mask:0xf
	v_add_f32_dpp v81, v76, v76 row_half_mirror row_mask:0xf bank_mask:0xf
	v_add_f32_dpp v82, v77, v77 row_half_mirror row_mask:0xf bank_mask:0xf
	v_add_f32_dpp v61, v60, v60 row_half_mirror row_mask:0xf bank_mask:0xf
	v_add_f32_dpp v36, v62, v62 row_mirror row_mask:0xf bank_mask:0xf
	v_add_f32_dpp v59, v63, v63 row_mirror row_mask:0xf bank_mask:0xf
	v_add_f32_dpp v67, v78, v78 row_mirror row_mask:0xf bank_mask:0xf
	v_add_f32_dpp v74, v79, v79 row_mirror row_mask:0xf bank_mask:0xf
	v_add_f32_dpp v75, v80, v80 row_mirror row_mask:0xf bank_mask:0xf
	v_add_f32_dpp v76, v81, v81 row_mirror row_mask:0xf bank_mask:0xf
	v_add_f32_dpp v77, v82, v82 row_mirror row_mask:0xf bank_mask:0xf
	v_add_f32_dpp v60, v61, v61 row_mirror row_mask:0xf bank_mask:0xf
	v_mov_b32_e32 v62, v36
	v_mov_b32_e32 v63, v59
	v_mov_b32_e32 v78, v67
	v_mov_b32_e32 v79, v74
	v_mov_b32_e32 v80, v75
	v_mov_b32_e32 v81, v76
	v_mov_b32_e32 v82, v77
	v_mov_b32_e32 v61, v60
	v_permlane16_swap_b32_e32 v62, v36
	v_permlane16_swap_b32_e32 v63, v59
	v_permlane16_swap_b32_e32 v78, v67
	v_permlane16_swap_b32_e32 v79, v74
	v_permlane16_swap_b32_e32 v80, v75
	v_permlane16_swap_b32_e32 v81, v76
	v_permlane16_swap_b32_e32 v82, v77
	v_permlane16_swap_b32_e32 v61, v60
	v_add_f32_e32 v62, v62, v36
	v_add_f32_e32 v63, v63, v59
	v_add_f32_e32 v78, v78, v67
	v_add_f32_e32 v79, v79, v74
	v_add_f32_e32 v80, v80, v75
	v_add_f32_e32 v81, v81, v76
	v_add_f32_e32 v82, v82, v77
	v_add_f32_e32 v61, v61, v60
	v_mov_b32_e32 v36, v62
; template <int LO, int HI> __global__ void __launch_bounds__(NWAVES * 64, 2) fox_fwd(Args args) {
;     ...
;                 fl[q] = wave_sum(a); }
;             float mine = fl[0];
; #pragma unroll
;             for (int q = 1; q < 8; ++q) mine = (lane == q) ? fl[q] : mine;
;             { const float z = mine + bfv; const float ls = fminf(z, 0.f) - log1pf(__expf(-fabsf(z)));
; #pragma unroll
;               for (int k = 0; k < 4; ++k)
; #pragma unroll
;                   for (int e = 0; e < 4; ++e) lsq[k][e] = (r == 4 * k + e) ? ls : lsq[k][e]; }
;         }
	v_mov_b32_e32 v59, v63
	v_mov_b32_e32 v67, v78
	v_mov_b32_e32 v74, v79
	v_mov_b32_e32 v75, v80
	v_mov_b32_e32 v76, v81
	v_mov_b32_e32 v77, v82
	v_mov_b32_e32 v60, v61
	v_permlane32_swap_b32_e32 v36, v62
	v_permlane32_swap_b32_e32 v59, v63
	v_permlane32_swap_b32_e32 v67, v78
	v_permlane32_swap_b32_e32 v74, v79
	v_permlane32_swap_b32_e32 v75, v80
	v_permlane32_swap_b32_e32 v76, v81
	v_permlane32_swap_b32_e32 v77, v82
	v_permlane32_swap_b32_e32 v60, v61
	v_add_f32_e32 v36, v36, v62
	v_add_f32_e32 v59, v59, v63
	v_add_f32_e32 v62, v67, v78
	v_add_f32_e32 v63, v74, v79
	v_add_f32_e32 v67, v75, v80
	v_add_f32_e32 v74, v76, v81
	v_add_f32_e32 v75, v77, v82
	v_add_f32_e32 v60, v60, v61
	v_cndmask_b32_e64 v36, v36, v59, s[4:5]
	v_cndmask_b32_e64 v36, v36, v62, s[6:7]
	v_cndmask_b32_e64 v36, v36, v63, s[8:9]
	v_cndmask_b32_e64 v36, v36, v67, s[10:11]
	v_cndmask_b32_e64 v36, v36, v74, s[12:13]
	v_cndmask_b32_e64 v36, v36, v75, s[14:15]
	v_cndmask_b32_e64 v36, v36, v60, s[16:17]
	v_add_f32_e32 v36, v71, v36
	v_min_f32_e32 v67, 0, v36
	v_mul_f32_e64 v36, |v36|, s29
	v_exp_f32_e32 v36, v36
	v_lshl_add_u64 v[56:57], v[56:57], 0, s[40:41]
	v_add_f32_e32 v59, 1.0, v36
	v_add_f32_e32 v62, -1.0, v59
	v_frexp_mant_f32_e32 v63, v59
	v_cvt_f64_f32_e32 v[60:61], v59
	v_sub_f32_e32 v74, v62, v59
	v_frexp_exp_i32_f64_e32 v60, v[60:61]
	v_cmp_gt_f32_e32 vcc, s37, v63
	v_sub_f32_e32 v62, v36, v62
	v_add_f32_e32 v61, 1.0, v74
	v_subbrev_co_u32_e32 v60, vcc, 0, v60, vcc
	v_add_f32_e32 v61, v62, v61
	v_sub_u32_e32 v62, 0, v60
	v_ldexp_f32 v59, v59, v62
	v_ldexp_f32 v61, v61, v62
	v_add_f32_e32 v62, -1.0, v59
	v_add_f32_e32 v74, 1.0, v59
	v_add_f32_e32 v63, 1.0, v62
	v_add_f32_e32 v75, -1.0, v74
	v_sub_f32_e32 v63, v59, v63
	v_sub_f32_e32 v59, v59, v75
	v_add_f32_e32 v59, v61, v59
	v_add_f32_e32 v75, v61, v63
	v_add_f32_e32 v61, v74, v59
	v_rcp_f32_e32 v78, v61
	v_add_f32_e32 v63, v62, v75
	v_sub_f32_e32 v74, v61, v74
	v_sub_f32_e32 v59, v59, v74
	v_mul_f32_e32 v80, v63, v78
	v_mul_f32_e32 v74, v61, v80
	v_fma_f32 v76, v80, v61, -v74
	v_sub_f32_e32 v62, v63, v62
	v_fmac_f32_e32 v76, v80, v59
	v_sub_f32_e32 v79, v75, v62
	v_add_f32_e32 v62, v74, v76
	v_sub_f32_e32 v75, v63, v62
	v_mov_b32_e32 v77, v62
	v_pk_add_f32 v[62:63], v[62:63], v[74:75] neg_lo:[0,1] neg_hi:[0,1]
	v_cvt_f32_i32_e32 v60, v60
	v_pk_add_f32 v[62:63], v[62:63], v[76:77] neg_lo:[0,1] neg_hi:[0,1]
	v_cmp_neq_f32_e32 vcc, s46, v36
	v_add_f32_e32 v63, v79, v63
	v_add_f32_e32 v62, v62, v63
	v_add_f32_e32 v63, v75, v62
	v_mul_f32_e32 v77, v78, v63
	v_mul_f32_e32 v74, v61, v77
	v_fma_f32 v76, v77, v61, -v74
	v_sub_f32_e32 v75, v75, v63
	v_fmac_f32_e32 v76, v77, v59
	v_add_f32_e32 v79, v62, v75
	v_add_f32_e32 v81, v80, v77
	v_add_f32_e32 v62, v74, v76
	v_sub_f32_e32 v61, v81, v80
	v_sub_f32_e32 v75, v63, v62
	v_sub_f32_e32 v59, v77, v61
	v_mov_b32_e32 v77, v62
	v_pk_add_f32 v[62:63], v[62:63], v[74:75] neg_lo:[0,1] neg_hi:[0,1]
	s_nop 0
	v_pk_add_f32 v[62:63], v[62:63], v[76:77] neg_lo:[0,1] neg_hi:[0,1]
	s_nop 0
	v_add_f32_e32 v61, v79, v63
	v_add_f32_e32 v61, v62, v61
	v_add_f32_e32 v61, v75, v61
	v_mul_f32_e32 v61, v78, v61
	v_add_f32_e32 v59, v59, v61
	v_add_f32_e32 v61, v81, v59
	v_mul_f32_e32 v62, v61, v61
	v_sub_f32_e32 v74, v61, v81
	v_fmamk_f32 v75, v62, 0x3e9b6dac, v20
	v_ldexp_f32 v63, v61, 1
	v_sub_f32_e32 v74, v59, v74
	v_mul_f32_e32 v61, v61, v62
	v_fmaak_f32 v59, v62, v75, 0x3f2aaada
	v_ldexp_f32 v77, v74, 1
	v_pk_mul_f32 v[74:75], v[60:61], v[58:59]
	s_nop 0
	v_fma_f32 v62, v60, s36, -v74
	v_fmac_f32_e32 v62, 0xb102e308, v60
	v_pk_add_f32 v[60:61], v[74:75], v[62:63]
	v_mov_b32_e32 v76, v74
	v_sub_f32_e32 v59, v61, v63
	v_sub_f32_e32 v59, v75, v59
	v_add_f32_e32 v77, v77, v59
	v_pk_add_f32 v[78:79], v[60:61], v[74:75] neg_lo:[0,1] neg_hi:[0,1]
	v_pk_add_f32 v[74:75], v[60:61], v[76:77]
	v_mov_b32_e32 v63, v60
	v_mov_b32_e32 v79, v75
	v_pk_add_f32 v[82:83], v[62:63], v[78:79] neg_lo:[0,1] neg_hi:[0,1]
	v_pk_add_f32 v[62:63], v[62:63], v[78:79]
	v_mov_b32_e32 v81, v60
	v_pk_add_f32 v[78:79], v[62:63], v[60:61] op_sel:[1,0] op_sel_hi:[0,1] neg_lo:[0,1] neg_hi:[0,1]
	v_mov_b32_e32 v80, v77
	v_mov_b32_e32 v76, v75
	v_mov_b32_e32 v77, v63
	v_pk_mov_b32 v[60:61], v[60:61], v[78:79] op_sel:[1,0]
	v_pk_add_f32 v[74:75], v[74:75], v[78:79] op_sel_hi:[1,0] neg_lo:[0,1] neg_hi:[0,1]
	v_pk_add_f32 v[60:61], v[76:77], v[60:61] neg_lo:[0,1] neg_hi:[0,1]
	v_mov_b32_e32 v74, v82
	v_pk_add_f32 v[60:61], v[80:81], v[60:61] neg_lo:[0,1] neg_hi:[0,1]
	v_mov_b32_e32 v83, v63
	v_pk_add_f32 v[74:75], v[74:75], v[60:61]
	s_nop 0
	v_pk_add_f32 v[76:77], v[74:75], v[74:75] op_sel:[0,1] op_sel_hi:[1,0]
	s_nop 0
	v_pk_add_f32 v[62:63], v[62:63], v[76:77] op_sel:[1,0] op_sel_hi:[0,1]
	v_mov_b32_e32 v75, v62
	v_mov_b32_e32 v61, v76
	v_pk_add_f32 v[76:77], v[74:75], v[82:83] neg_lo:[0,1] neg_hi:[0,1]
	s_nop 0
	v_sub_f32_e32 v59, v74, v76
	v_pk_add_f32 v[60:61], v[60:61], v[76:77] neg_lo:[0,1] neg_hi:[0,1]
	v_sub_f32_e32 v59, v82, v59
	v_add_f32_e32 v59, v60, v59
	v_add_f32_e32 v59, v59, v61
	v_add_f32_e32 v59, v62, v59
	v_cndmask_b32_e32 v59, v64, v59, vcc
	v_cmp_ngt_f32_e32 vcc, -1.0, v36
	s_nop 1
	v_cndmask_b32_e32 v59, v65, v59, vcc
	v_cmp_neq_f32_e32 vcc, -1.0, v36
	s_nop 1
	v_cndmask_b32_e32 v59, v66, v59, vcc
	v_cmp_lt_f32_e64 vcc, |v36|, s47
	s_nop 1
	v_cndmask_b32_e32 v36, v59, v36, vcc
	v_sub_f32_e32 v36, v67, v36
	s_cselect_b64 vcc, -1, 0
	s_cmpk_eq_i32 s30, 0x1000
	v_cndmask_b32_e32 v37, v37, v36, vcc
	s_cselect_b64 vcc, -1, 0
	s_cmpk_eq_i32 s30, 0x2000
	v_cndmask_b32_e32 v21, v21, v36, vcc
	s_cselect_b64 vcc, -1, 0
	s_cmpk_eq_i32 s30, 0x3000
	v_cndmask_b32_e32 v30, v30, v36, vcc
	s_cselect_b64 vcc, -1, 0
	s_cmpk_eq_i32 s30, 0x4000
	v_cndmask_b32_e32 v31, v31, v36, vcc
	s_cselect_b64 vcc, -1, 0
	s_cmpk_eq_i32 s30, 0x5000
	v_cndmask_b32_e32 v32, v32, v36, vcc
	s_cselect_b64 vcc, -1, 0
	s_cmpk_eq_i32 s30, 0x6000
	v_cndmask_b32_e32 v33, v33, v36, vcc
	s_cselect_b64 vcc, -1, 0
	s_cmpk_eq_i32 s30, 0x7000
	v_cndmask_b32_e32 v26, v26, v36, vcc
	s_cselect_b64 vcc, -1, 0
	s_cmpk_eq_u32 s30, 0x8000
	v_cndmask_b32_e32 v27, v27, v36, vcc
	s_cselect_b64 vcc, -1, 0
	s_cmpk_eq_u32 s30, 0x9000
	v_cndmask_b32_e32 v28, v28, v36, vcc
	s_cselect_b64 vcc, -1, 0
	s_cmpk_eq_u32 s30, 0xa000
	v_cndmask_b32_e32 v29, v29, v36, vcc
	s_cselect_b64 vcc, -1, 0
	s_cmpk_eq_u32 s30, 0xb000
	v_cndmask_b32_e32 v22, v22, v36, vcc
	s_cselect_b64 vcc, -1, 0
	s_cmpk_eq_u32 s30, 0xc000
	v_cndmask_b32_e32 v23, v23, v36, vcc
	s_cselect_b64 vcc, -1, 0
	s_cmpk_eq_u32 s30, 0xd000
	v_cndmask_b32_e32 v24, v24, v36, vcc
	s_cselect_b64 vcc, -1, 0
	s_add_u32 s30, s30, 0x1000
	s_addc_u32 s31, s31, 0
	s_cmpk_eq_u32 s30, 0xe000
	v_cndmask_b32_e32 v25, v25, v36, vcc
	s_cbranch_scc0 .LBB0_131
; template <int LO, int HI> __global__ void __launch_bounds__(NWAVES * 64, 2) fox_fwd(Args args) {
;     ...
;         }
;         if (lane < 8) { f32x4* dst = (f32x4*)(LF + (size_t)(b * 8 + lane) * T + (m0 - b * T));
; #pragma unroll
;             for (int k = 0; k < 4; ++k) dst[k] = lsq[k]; }
	s_mov_b32 m0, s52
	s_barrier
	v_cmp_gt_u32_e32 vcc, 8, v1
	s_and_saveexec_b64 s[4:5], vcc
	s_cbranch_execz .LBB0_134
	v_lshl_or_b32 v2, s44, 3, v1
	v_ashrrev_i32_e32 v3, 31, v2
	s_lshl_b32 s6, s44, 12
	v_lshlrev_b64 v[2:3], 14, v[2:3]
	s_sub_i32 s6, s28, s6
	v_lshl_add_u64 v[2:3], s[26:27], 0, v[2:3]
	s_ashr_i32 s7, s6, 31
	v_lshl_add_u64 v[2:3], s[6:7], 2, v[2:3]
	s_mov_b64 s[6:7], 0x100000
	v_lshl_add_u64 v[4:5], v[2:3], 0, s[6:7]
	v_add_co_u32_e32 v2, vcc, 0x100000, v2
	v_mov_b32_e32 v20, v37
	s_nop 0
	v_addc_co_u32_e32 v3, vcc, 0, v3, vcc
	global_store_dwordx4 v[2:3], v[18:21], off
	global_store_dwordx4 v[4:5], v[30:33], off offset:16
	global_store_dwordx4 v[4:5], v[26:29], off offset:32
	global_store_dwordx4 v[4:5], v[22:25], off offset:48
